# stack + p3 hoist + acc v_mov_b64 + drop duplicated lgkmcnt(0) at MFMA block heads
# speedup vs baseline: 1.0122x; 1.0011x over previous
.LBB0_124:
	ds_read_b128 v[160:163], v202
	ds_read_b128 v[164:167], v202 offset:1024
	ds_read_b128 v[168:171], v202 offset:2048
	ds_read_b128 v[172:175], v202 offset:3072
	ds_read_b128 v[208:211], v203
	ds_read_b128 v[212:215], v203 offset:1024
	ds_read_b128 v[218:221], v203 offset:2048
	ds_read_b128 v[222:225], v203 offset:3072
	s_add_i32 s15, s14, 2
	s_add_u32 s10, s12, s6
	s_addc_u32 s11, s13, s7
	s_cmpk_eq_i32 s6, 0x700
	s_cselect_b32 s16, s85, s9
	s_cselect_b32 s17, s84, s8
	s_cselect_b32 s86, 0, s15
	s_cselect_b32 s11, s57, s11
	s_cselect_b32 s10, s56, s10
	v_lshl_add_u64 v[192:193], v[156:157], 0, s[6:7]
	s_add_i32 m0, s39, 0xc000
	ds_read_b128 v[226:229], v204
	ds_read_b128 v[230:233], v204 offset:1024
	ds_read_b128 v[234:237], v204 offset:2048
	ds_read_b128 v[238:241], v204 offset:3072
	ds_read_b128 v[242:245], v204 offset:4096
	ds_read_b128 v[246:249], v204 offset:5120
	ds_read_b128 v[250:253], v204 offset:6144
	ds_read_b128 v[186:189], v204 offset:7168
	global_load_lds_dwordx4 v[192:193], off
	v_lshl_add_u64 v[192:193], v[158:159], 0, s[6:7]
	s_add_i32 m0, s39, 0xe000
	s_nop 0
	global_load_lds_dwordx4 v[192:193], off
	s_waitcnt vmcnt(8)
	s_waitcnt lgkmcnt(0)
	s_barrier
	s_setprio 1
	v_mfma_f32_16x16x32_bf16 v[124:127], v[160:163], v[226:229], v[124:127]
	v_mfma_f32_16x16x32_bf16 v[120:123], v[168:171], v[226:229], v[120:123]
	v_mfma_f32_16x16x32_bf16 v[108:111], v[160:163], v[234:237], v[108:111]
	v_mfma_f32_16x16x32_bf16 v[104:107], v[168:171], v[234:237], v[104:107]
	v_mfma_f32_16x16x32_bf16 v[92:95], v[160:163], v[242:245], v[92:95]
	v_mfma_f32_16x16x32_bf16 v[88:91], v[168:171], v[242:245], v[88:91]
	v_mfma_f32_16x16x32_bf16 v[76:79], v[160:163], v[250:253], v[76:79]
	v_mfma_f32_16x16x32_bf16 v[72:75], v[168:171], v[250:253], v[72:75]
	v_mfma_f32_16x16x32_bf16 v[124:127], v[164:167], v[230:233], v[124:127]
	v_mfma_f32_16x16x32_bf16 v[120:123], v[172:175], v[230:233], v[120:123]
	v_mfma_f32_16x16x32_bf16 v[108:111], v[164:167], v[238:241], v[108:111]
	v_mfma_f32_16x16x32_bf16 v[104:107], v[172:175], v[238:241], v[104:107]
	v_mfma_f32_16x16x32_bf16 v[92:95], v[164:167], v[246:249], v[92:95]
	v_mfma_f32_16x16x32_bf16 v[88:91], v[172:175], v[246:249], v[88:91]
	v_mfma_f32_16x16x32_bf16 v[76:79], v[164:167], v[186:189], v[76:79]
	v_mfma_f32_16x16x32_bf16 v[72:75], v[172:175], v[186:189], v[72:75]
	s_setprio 0
	s_setprio 1
	v_mfma_f32_16x16x32_bf16 v[116:119], v[208:211], v[226:229], v[116:119]
	v_mfma_f32_16x16x32_bf16 v[112:115], v[218:221], v[226:229], v[112:115]
	v_mfma_f32_16x16x32_bf16 v[100:103], v[208:211], v[234:237], v[100:103]
	v_mfma_f32_16x16x32_bf16 v[96:99], v[218:221], v[234:237], v[96:99]
	v_mfma_f32_16x16x32_bf16 v[84:87], v[208:211], v[242:245], v[84:87]
	v_mfma_f32_16x16x32_bf16 v[80:83], v[218:221], v[242:245], v[80:83]
	v_mfma_f32_16x16x32_bf16 v[68:71], v[208:211], v[250:253], v[68:71]
	v_mfma_f32_16x16x32_bf16 v[64:67], v[218:221], v[250:253], v[64:67]
	v_mfma_f32_16x16x32_bf16 v[116:119], v[212:215], v[230:233], v[116:119]
	v_mfma_f32_16x16x32_bf16 v[112:115], v[222:225], v[230:233], v[112:115]
	v_mfma_f32_16x16x32_bf16 v[100:103], v[212:215], v[238:241], v[100:103]
	v_mfma_f32_16x16x32_bf16 v[96:99], v[222:225], v[238:241], v[96:99]
	v_mfma_f32_16x16x32_bf16 v[84:87], v[212:215], v[246:249], v[84:87]
	v_mfma_f32_16x16x32_bf16 v[80:83], v[222:225], v[246:249], v[80:83]
	v_mfma_f32_16x16x32_bf16 v[68:71], v[212:215], v[186:189], v[68:71]
	v_mfma_f32_16x16x32_bf16 v[64:67], v[222:225], v[186:189], v[64:67]
	s_setprio 0
	s_barrier
	s_add_i32 s18, s94, s97
	v_lshl_add_u64 v[192:193], s[10:11], 0, v[132:133]
	s_mov_b32 m0, s18
	ds_read_b128 v[186:189], v204 offset:16384
	ds_read_b128 v[226:229], v204 offset:17408
	ds_read_b128 v[230:233], v204 offset:18432
	ds_read_b128 v[234:237], v204 offset:19456
	ds_read_b128 v[238:241], v204 offset:20480
	ds_read_b128 v[242:245], v204 offset:21504
	ds_read_b128 v[246:249], v204 offset:22528
	ds_read_b128 v[250:253], v204 offset:23552
	global_load_lds_dwordx4 v[192:193], off
	s_add_i32 m0, s18, 0x2000
	s_add_u32 s18, s10, 0x40000
	v_lshl_add_u64 v[196:197], s[10:11], 0, v[136:137]
	s_addc_u32 s19, s11, 0
	s_add_i32 s20, s95, s97
	global_load_lds_dwordx4 v[196:197], off
	v_lshl_add_u64 v[176:177], s[18:19], 0, v[132:133]
	s_mov_b32 m0, s20
	s_nop 0
	global_load_lds_dwordx4 v[176:177], off
	v_lshl_add_u64 v[176:177], s[18:19], 0, v[136:137]
	s_add_i32 m0, s20, 0x2000
	s_lshl_b64 s[18:19], s[86:87], 7
	s_add_u32 s18, s17, s18
	s_addc_u32 s19, s16, s19
	global_load_lds_dwordx4 v[176:177], off
	v_lshl_add_u64 v[176:177], s[18:19], 0, v[130:131]
	s_mov_b32 m0, s39
	s_nop 0
	global_load_lds_dwordx4 v[176:177], off
	v_lshl_add_u64 v[176:177], s[18:19], 0, v[134:135]
	s_mov_b32 m0, s91
	s_nop 0
	global_load_lds_dwordx4 v[176:177], off
	s_waitcnt vmcnt(8)
	s_waitcnt lgkmcnt(0)
	s_barrier
	s_setprio 1
	v_mfma_f32_16x16x32_bf16 v[60:63], v[160:163], v[186:189], v[60:63]
	v_mfma_f32_16x16x32_bf16 v[56:59], v[168:171], v[186:189], v[56:59]
	v_mfma_f32_16x16x32_bf16 v[44:47], v[160:163], v[230:233], v[44:47]
	v_mfma_f32_16x16x32_bf16 v[40:43], v[168:171], v[230:233], v[40:43]
	v_mfma_f32_16x16x32_bf16 v[28:31], v[160:163], v[238:241], v[28:31]
	v_mfma_f32_16x16x32_bf16 v[24:27], v[168:171], v[238:241], v[24:27]
	v_mfma_f32_16x16x32_bf16 v[12:15], v[160:163], v[246:249], v[12:15]
	v_mfma_f32_16x16x32_bf16 v[8:11], v[168:171], v[246:249], v[8:11]
	v_mfma_f32_16x16x32_bf16 v[60:63], v[164:167], v[226:229], v[60:63]
	v_mfma_f32_16x16x32_bf16 v[56:59], v[172:175], v[226:229], v[56:59]
	v_mfma_f32_16x16x32_bf16 v[44:47], v[164:167], v[234:237], v[44:47]
	v_mfma_f32_16x16x32_bf16 v[40:43], v[172:175], v[234:237], v[40:43]
	v_mfma_f32_16x16x32_bf16 v[28:31], v[164:167], v[242:245], v[28:31]
	v_mfma_f32_16x16x32_bf16 v[24:27], v[172:175], v[242:245], v[24:27]
	v_mfma_f32_16x16x32_bf16 v[12:15], v[164:167], v[250:253], v[12:15]
	v_mfma_f32_16x16x32_bf16 v[8:11], v[172:175], v[250:253], v[8:11]
	s_setprio 0
	s_setprio 1
	v_mfma_f32_16x16x32_bf16 v[52:55], v[208:211], v[186:189], v[52:55]
	v_mfma_f32_16x16x32_bf16 v[48:51], v[218:221], v[186:189], v[48:51]
	v_mfma_f32_16x16x32_bf16 v[36:39], v[208:211], v[230:233], v[36:39]
	v_mfma_f32_16x16x32_bf16 v[32:35], v[218:221], v[230:233], v[32:35]
	v_mfma_f32_16x16x32_bf16 v[20:23], v[208:211], v[238:241], v[20:23]
	v_mfma_f32_16x16x32_bf16 v[16:19], v[218:221], v[238:241], v[16:19]
	v_mfma_f32_16x16x32_bf16 v[4:7], v[208:211], v[246:249], v[4:7]
	v_mfma_f32_16x16x32_bf16 v[0:3], v[218:221], v[246:249], v[0:3]
	v_mfma_f32_16x16x32_bf16 v[52:55], v[212:215], v[226:229], v[52:55]
	v_mfma_f32_16x16x32_bf16 v[48:51], v[222:225], v[226:229], v[48:51]
	v_mfma_f32_16x16x32_bf16 v[36:39], v[212:215], v[234:237], v[36:39]
	v_mfma_f32_16x16x32_bf16 v[32:35], v[222:225], v[234:237], v[32:35]
	v_mfma_f32_16x16x32_bf16 v[20:23], v[212:215], v[242:245], v[20:23]
	v_mfma_f32_16x16x32_bf16 v[16:19], v[222:225], v[242:245], v[16:19]
	v_mfma_f32_16x16x32_bf16 v[4:7], v[212:215], v[250:253], v[4:7]
	v_mfma_f32_16x16x32_bf16 v[0:3], v[222:225], v[250:253], v[0:3]
	s_setprio 0
	s_barrier
	s_add_i32 s20, 0, 0x18000
	v_add_u32_e32 v138, s20, v179
	s_add_i32 s21, 0, 0x1c000
	ds_read_b128 v[160:163], v138
	ds_read_b128 v[164:167], v138 offset:1024
	ds_read_b128 v[168:171], v138 offset:2048
	ds_read_b128 v[172:175], v138 offset:3072
	v_add_u32_e32 v138, s21, v179
	ds_read_b128 v[186:189], v138
	ds_read_b128 v[208:211], v138 offset:1024
	ds_read_b128 v[212:215], v138 offset:2048
	ds_read_b128 v[218:221], v138 offset:3072
	s_add_u32 s18, s18, 0x40000
	s_addc_u32 s19, s19, 0
	s_mov_b32 m0, s33
	v_lshl_add_u64 v[176:177], s[18:19], 0, v[130:131]
	ds_read_b128 v[222:225], v204 offset:32768
	ds_read_b128 v[226:229], v204 offset:33792
	ds_read_b128 v[230:233], v204 offset:34816
	ds_read_b128 v[234:237], v204 offset:35840
	ds_read_b128 v[238:241], v204 offset:36864
	ds_read_b128 v[242:245], v204 offset:37888
	ds_read_b128 v[246:249], v204 offset:38912
	ds_read_b128 v[250:253], v204 offset:39936
	global_load_lds_dwordx4 v[176:177], off
	v_lshl_add_u64 v[176:177], s[18:19], 0, v[134:135]
	s_mov_b32 m0, s58
	s_nop 0
	global_load_lds_dwordx4 v[176:177], off
	s_waitcnt vmcnt(8)
	s_waitcnt lgkmcnt(0)
	s_barrier
	s_setprio 1
	v_mfma_f32_16x16x32_bf16 v[124:127], v[160:163], v[222:225], v[124:127]
	v_mfma_f32_16x16x32_bf16 v[120:123], v[168:171], v[222:225], v[120:123]
	v_mfma_f32_16x16x32_bf16 v[108:111], v[160:163], v[230:233], v[108:111]
	v_mfma_f32_16x16x32_bf16 v[104:107], v[168:171], v[230:233], v[104:107]
	v_mfma_f32_16x16x32_bf16 v[92:95], v[160:163], v[238:241], v[92:95]
	v_mfma_f32_16x16x32_bf16 v[88:91], v[168:171], v[238:241], v[88:91]
	v_mfma_f32_16x16x32_bf16 v[76:79], v[160:163], v[246:249], v[76:79]
	v_mfma_f32_16x16x32_bf16 v[72:75], v[168:171], v[246:249], v[72:75]
	v_mfma_f32_16x16x32_bf16 v[124:127], v[164:167], v[226:229], v[124:127]
	v_mfma_f32_16x16x32_bf16 v[120:123], v[172:175], v[226:229], v[120:123]
	v_mfma_f32_16x16x32_bf16 v[108:111], v[164:167], v[234:237], v[108:111]
	v_mfma_f32_16x16x32_bf16 v[104:107], v[172:175], v[234:237], v[104:107]
	v_mfma_f32_16x16x32_bf16 v[92:95], v[164:167], v[242:245], v[92:95]
	v_mfma_f32_16x16x32_bf16 v[88:91], v[172:175], v[242:245], v[88:91]
	v_mfma_f32_16x16x32_bf16 v[76:79], v[164:167], v[250:253], v[76:79]
	v_mfma_f32_16x16x32_bf16 v[72:75], v[172:175], v[250:253], v[72:75]
	s_setprio 0
	s_setprio 1
	v_mfma_f32_16x16x32_bf16 v[116:119], v[186:189], v[222:225], v[116:119]
	v_mfma_f32_16x16x32_bf16 v[112:115], v[212:215], v[222:225], v[112:115]
	v_mfma_f32_16x16x32_bf16 v[100:103], v[186:189], v[230:233], v[100:103]
	v_mfma_f32_16x16x32_bf16 v[96:99], v[212:215], v[230:233], v[96:99]
	v_mfma_f32_16x16x32_bf16 v[84:87], v[186:189], v[238:241], v[84:87]
	v_mfma_f32_16x16x32_bf16 v[80:83], v[212:215], v[238:241], v[80:83]
	v_mfma_f32_16x16x32_bf16 v[68:71], v[186:189], v[246:249], v[68:71]
	v_mfma_f32_16x16x32_bf16 v[64:67], v[212:215], v[246:249], v[64:67]
	v_mfma_f32_16x16x32_bf16 v[116:119], v[208:211], v[226:229], v[116:119]
	v_mfma_f32_16x16x32_bf16 v[112:115], v[218:221], v[226:229], v[112:115]
	v_mfma_f32_16x16x32_bf16 v[100:103], v[208:211], v[234:237], v[100:103]
	v_mfma_f32_16x16x32_bf16 v[96:99], v[218:221], v[234:237], v[96:99]
	v_mfma_f32_16x16x32_bf16 v[84:87], v[208:211], v[242:245], v[84:87]
	v_mfma_f32_16x16x32_bf16 v[80:83], v[218:221], v[242:245], v[80:83]
	v_mfma_f32_16x16x32_bf16 v[68:71], v[208:211], v[250:253], v[68:71]
	v_mfma_f32_16x16x32_bf16 v[64:67], v[218:221], v[250:253], v[64:67]
	s_setprio 0
	s_barrier
	s_add_i32 s18, s20, s97
	v_lshl_add_u64 v[176:177], v[192:193], 0, s[64:65]
	s_mov_b32 m0, s18
	ds_read_b128 v[222:225], v204 offset:49152
	ds_read_b128 v[226:229], v204 offset:50176
	ds_read_b128 v[230:233], v204 offset:51200
	ds_read_b128 v[234:237], v204 offset:52224
	ds_read_b128 v[238:241], v204 offset:53248
	ds_read_b128 v[242:245], v204 offset:54272
	ds_read_b128 v[246:249], v204 offset:55296
	ds_read_b128 v[250:253], v204 offset:56320
	global_load_lds_dwordx4 v[176:177], off
	s_add_i32 m0, s18, 0x2000
	s_add_u32 s10, s10, 0x40080
	v_lshl_add_u64 v[176:177], v[196:197], 0, s[64:65]
	s_addc_u32 s11, s11, 0
	s_add_i32 s18, s21, s97
	global_load_lds_dwordx4 v[176:177], off
	v_lshl_add_u64 v[176:177], s[10:11], 0, v[132:133]
	s_mov_b32 m0, s18
	s_or_b32 s86, s86, 1
	global_load_lds_dwordx4 v[176:177], off
	v_lshl_add_u64 v[176:177], s[10:11], 0, v[136:137]
	s_add_i32 m0, s18, 0x2000
	s_lshl_b64 s[10:11], s[86:87], 7
	s_add_u32 s10, s17, s10
	s_addc_u32 s11, s16, s11
	global_load_lds_dwordx4 v[176:177], off
	v_lshl_add_u64 v[176:177], s[10:11], 0, v[130:131]
	s_mov_b32 m0, s92
	s_nop 0
	global_load_lds_dwordx4 v[176:177], off
	v_lshl_add_u64 v[176:177], s[10:11], 0, v[134:135]
	s_mov_b32 m0, s93
	s_nop 0
	global_load_lds_dwordx4 v[176:177], off
	s_waitcnt vmcnt(8)
	s_waitcnt lgkmcnt(0)
	s_barrier
	s_setprio 1
	v_mfma_f32_16x16x32_bf16 v[60:63], v[160:163], v[222:225], v[60:63]
	v_mfma_f32_16x16x32_bf16 v[56:59], v[168:171], v[222:225], v[56:59]
	v_mfma_f32_16x16x32_bf16 v[44:47], v[160:163], v[230:233], v[44:47]
	v_mfma_f32_16x16x32_bf16 v[40:43], v[168:171], v[230:233], v[40:43]
	v_mfma_f32_16x16x32_bf16 v[28:31], v[160:163], v[238:241], v[28:31]
	v_mfma_f32_16x16x32_bf16 v[24:27], v[168:171], v[238:241], v[24:27]
	v_mfma_f32_16x16x32_bf16 v[12:15], v[160:163], v[246:249], v[12:15]
	v_mfma_f32_16x16x32_bf16 v[8:11], v[168:171], v[246:249], v[8:11]
	v_mfma_f32_16x16x32_bf16 v[60:63], v[164:167], v[226:229], v[60:63]
	v_mfma_f32_16x16x32_bf16 v[56:59], v[172:175], v[226:229], v[56:59]
	v_mfma_f32_16x16x32_bf16 v[44:47], v[164:167], v[234:237], v[44:47]
	v_mfma_f32_16x16x32_bf16 v[40:43], v[172:175], v[234:237], v[40:43]
	v_mfma_f32_16x16x32_bf16 v[28:31], v[164:167], v[242:245], v[28:31]
	v_mfma_f32_16x16x32_bf16 v[24:27], v[172:175], v[242:245], v[24:27]
	v_mfma_f32_16x16x32_bf16 v[12:15], v[164:167], v[250:253], v[12:15]
	v_mfma_f32_16x16x32_bf16 v[8:11], v[172:175], v[250:253], v[8:11]
	s_setprio 0
	s_setprio 1
	v_mfma_f32_16x16x32_bf16 v[52:55], v[186:189], v[222:225], v[52:55]
	v_mfma_f32_16x16x32_bf16 v[48:51], v[212:215], v[222:225], v[48:51]
	v_mfma_f32_16x16x32_bf16 v[36:39], v[186:189], v[230:233], v[36:39]
	v_mfma_f32_16x16x32_bf16 v[32:35], v[212:215], v[230:233], v[32:35]
	v_mfma_f32_16x16x32_bf16 v[20:23], v[186:189], v[238:241], v[20:23]
	v_mfma_f32_16x16x32_bf16 v[16:19], v[212:215], v[238:241], v[16:19]
	v_mfma_f32_16x16x32_bf16 v[4:7], v[186:189], v[246:249], v[4:7]
	v_mfma_f32_16x16x32_bf16 v[0:3], v[212:215], v[246:249], v[0:3]
	v_mfma_f32_16x16x32_bf16 v[52:55], v[208:211], v[226:229], v[52:55]
	v_mfma_f32_16x16x32_bf16 v[48:51], v[218:221], v[226:229], v[48:51]
	v_mfma_f32_16x16x32_bf16 v[36:39], v[208:211], v[234:237], v[36:39]
	v_mfma_f32_16x16x32_bf16 v[32:35], v[218:221], v[234:237], v[32:35]
	v_mfma_f32_16x16x32_bf16 v[20:23], v[208:211], v[242:245], v[20:23]
	v_mfma_f32_16x16x32_bf16 v[16:19], v[218:221], v[242:245], v[16:19]
	v_mfma_f32_16x16x32_bf16 v[4:7], v[208:211], v[250:253], v[4:7]
	v_mfma_f32_16x16x32_bf16 v[0:3], v[218:221], v[250:253], v[0:3]
	s_setprio 0
	s_barrier
	s_add_u32 s6, s6, 0x100
	s_addc_u32 s7, s7, 0
	s_cmp_gt_u32 s14, 13
	s_mov_b32 s14, s15
	s_cbranch_scc0 .LBB0_124
	s_and_b64 vcc, exec, s[66:67]
	s_cbranch_vccz .LBB0_127
	s_barrier

.LBB0_425:
	s_add_u32 s12, s30, s38
	s_addc_u32 s42, s31, s39
	s_add_u32 s12, s12, 0xfff80080
	s_addc_u32 s65, s42, -1
	s_cmp_eq_u32 s64, 30
	s_cselect_b64 s[42:43], -1, 0
	s_and_b64 s[42:43], s[42:43], exec
	s_cselect_b32 s43, s19, s65
	s_cselect_b32 s42, s21, s12
	s_add_i32 s65, s64, 2
	s_cmp_eq_u32 s64, 30
	s_cselect_b64 s[66:67], -1, 0
	s_and_b64 s[68:69], s[66:67], exec
	s_cselect_b32 s12, 0, s65
	s_and_b64 s[66:67], s[66:67], s[4:5]
	s_and_b64 s[66:67], s[66:67], exec
	s_cselect_b32 s68, s23, s35
	s_cselect_b32 s69, s22, s34
	s_cselect_b32 s66, s27, s37
	s_cselect_b32 s67, s26, s36
	v_lshl_add_u64 v[214:215], s[44:45], 0, v[214:215]
	s_add_i32 m0, s29, 0xc000
	v_lshl_add_u64 v[2:3], s[44:45], 0, v[2:3]
	global_load_lds_dwordx4 v[214:215], off
	s_add_i32 m0, s29, 0xe000
	s_nop 0
	global_load_lds_dwordx4 v[2:3], off
	s_waitcnt vmcnt(8)
	s_waitcnt lgkmcnt(0)
	s_barrier
	s_setprio 1
	v_mfma_f32_16x16x32_bf16 v[128:131], v[148:151], v[188:191], v[128:131]
	v_mfma_f32_16x16x32_bf16 v[124:127], v[156:159], v[188:191], v[124:127]
	v_mfma_f32_16x16x32_bf16 v[112:115], v[148:151], v[180:183], v[112:115]
	v_mfma_f32_16x16x32_bf16 v[108:111], v[156:159], v[180:183], v[108:111]
	v_mfma_f32_16x16x32_bf16 v[96:99], v[148:151], v[172:175], v[96:99]
	v_mfma_f32_16x16x32_bf16 v[92:95], v[156:159], v[172:175], v[92:95]
	v_mfma_f32_16x16x32_bf16 v[80:83], v[148:151], v[164:167], v[80:83]
	v_mfma_f32_16x16x32_bf16 v[76:79], v[156:159], v[164:167], v[76:79]
	v_mfma_f32_16x16x32_bf16 v[128:131], v[152:155], v[192:195], v[128:131]
	v_mfma_f32_16x16x32_bf16 v[124:127], v[160:163], v[192:195], v[124:127]
	v_mfma_f32_16x16x32_bf16 v[112:115], v[152:155], v[184:187], v[112:115]
	v_mfma_f32_16x16x32_bf16 v[108:111], v[160:163], v[184:187], v[108:111]
	v_mfma_f32_16x16x32_bf16 v[96:99], v[152:155], v[176:179], v[96:99]
	v_mfma_f32_16x16x32_bf16 v[92:95], v[160:163], v[176:179], v[92:95]
	v_mfma_f32_16x16x32_bf16 v[80:83], v[152:155], v[168:171], v[80:83]
	v_mfma_f32_16x16x32_bf16 v[76:79], v[160:163], v[168:171], v[76:79]
	s_setprio 0
	s_setprio 1
	v_mfma_f32_16x16x32_bf16 v[120:123], v[132:135], v[188:191], v[120:123]
	v_mfma_f32_16x16x32_bf16 v[116:119], v[140:143], v[188:191], v[116:119]
	v_mfma_f32_16x16x32_bf16 v[104:107], v[132:135], v[180:183], v[104:107]
	v_mfma_f32_16x16x32_bf16 v[100:103], v[140:143], v[180:183], v[100:103]
	v_mfma_f32_16x16x32_bf16 v[88:91], v[132:135], v[172:175], v[88:91]
	v_mfma_f32_16x16x32_bf16 v[84:87], v[140:143], v[172:175], v[84:87]
	v_mfma_f32_16x16x32_bf16 v[72:75], v[132:135], v[164:167], v[72:75]
	v_mfma_f32_16x16x32_bf16 v[68:71], v[140:143], v[164:167], v[68:71]
	v_mfma_f32_16x16x32_bf16 v[120:123], v[136:139], v[192:195], v[120:123]
	v_mfma_f32_16x16x32_bf16 v[116:119], v[144:147], v[192:195], v[116:119]
	v_mfma_f32_16x16x32_bf16 v[104:107], v[136:139], v[184:187], v[104:107]
	v_mfma_f32_16x16x32_bf16 v[100:103], v[144:147], v[184:187], v[100:103]
	v_mfma_f32_16x16x32_bf16 v[88:91], v[136:139], v[176:179], v[88:91]
	v_mfma_f32_16x16x32_bf16 v[84:87], v[144:147], v[176:179], v[84:87]
	v_mfma_f32_16x16x32_bf16 v[72:75], v[136:139], v[168:171], v[72:75]
	v_mfma_f32_16x16x32_bf16 v[68:71], v[144:147], v[168:171], v[68:71]
	s_setprio 0
	s_barrier
	s_mov_b32 m0, s47
	v_lshl_add_u64 v[214:215], s[42:43], 0, v[198:199]
	s_add_u32 s44, s42, 0x80000
	ds_read_b128 v[164:167], v219 offset:16384
	ds_read_b128 v[168:171], v219 offset:17408
	ds_read_b128 v[172:175], v219 offset:18432
	ds_read_b128 v[176:179], v219 offset:19456
	ds_read_b128 v[180:183], v219 offset:20480
	ds_read_b128 v[184:187], v219 offset:21504
	ds_read_b128 v[188:191], v219 offset:22528
	ds_read_b128 v[192:195], v219 offset:23552
	global_load_lds_dwordx4 v[214:215], off
	v_lshl_add_u64 v[220:221], s[42:43], 0, v[202:203]
	s_mov_b32 m0, s48
	s_addc_u32 s45, s43, 0
	global_load_lds_dwordx4 v[220:221], off
	v_lshl_add_u64 v[2:3], s[44:45], 0, v[198:199]
	s_mov_b32 m0, s49
	s_add_i32 s70, s12, -8
	global_load_lds_dwordx4 v[2:3], off
	v_lshl_add_u64 v[2:3], s[44:45], 0, v[202:203]
	s_lshl_b64 s[44:45], s[12:13], 7
	s_add_u32 s71, s69, s44
	s_addc_u32 s72, s68, s45
	s_lshl_b32 s44, s70, 19
	s_add_u32 s73, s67, s44
	s_addc_u32 s74, s66, 0
	s_add_i32 s75, 0, 0x18000
	s_add_i32 s76, 0, 0x1c000
	s_add_u32 s77, s71, 0x80000
	s_addc_u32 s84, s72, 0
	s_add_u32 s85, s73, 0x800
	s_addc_u32 s86, s74, 0
	s_cmp_lt_u32 s70, 16
	s_cselect_b64 vcc, -1, 0
	s_and_b64 s[44:45], vcc, exec
	s_mov_b32 m0, s50
	v_cndmask_b32_e32 v222, v196, v204, vcc
	v_mov_b32_e32 v223, v1
	s_cselect_b32 s45, s74, s72
	s_cselect_b32 s44, s73, s71
	global_load_lds_dwordx4 v[2:3], off
	v_cndmask_b32_e32 v0, v200, v206, vcc
	v_lshl_add_u64 v[2:3], s[44:45], 0, v[222:223]
	s_mov_b32 m0, s29
	s_nop 0
	global_load_lds_dwordx4 v[2:3], off
	v_lshl_add_u64 v[2:3], s[44:45], 0, v[0:1]
	s_mov_b32 m0, s51
	s_nop 0
	global_load_lds_dwordx4 v[2:3], off
	s_waitcnt vmcnt(8)
	s_waitcnt lgkmcnt(0)
	s_barrier
	s_setprio 1
	v_mfma_f32_16x16x32_bf16 v[64:67], v[148:151], v[164:167], v[64:67]
	v_mfma_f32_16x16x32_bf16 v[60:63], v[156:159], v[164:167], v[60:63]
	v_mfma_f32_16x16x32_bf16 v[48:51], v[148:151], v[172:175], v[48:51]
	v_mfma_f32_16x16x32_bf16 v[44:47], v[156:159], v[172:175], v[44:47]
	v_mfma_f32_16x16x32_bf16 v[32:35], v[148:151], v[180:183], v[32:35]
	v_mfma_f32_16x16x32_bf16 v[28:31], v[156:159], v[180:183], v[28:31]
	v_mfma_f32_16x16x32_bf16 v[16:19], v[148:151], v[188:191], v[16:19]
	v_mfma_f32_16x16x32_bf16 v[12:15], v[156:159], v[188:191], v[12:15]
	v_mfma_f32_16x16x32_bf16 v[64:67], v[152:155], v[168:171], v[64:67]
	v_mfma_f32_16x16x32_bf16 v[60:63], v[160:163], v[168:171], v[60:63]
	v_mfma_f32_16x16x32_bf16 v[48:51], v[152:155], v[176:179], v[48:51]
	v_mfma_f32_16x16x32_bf16 v[44:47], v[160:163], v[176:179], v[44:47]
	v_mfma_f32_16x16x32_bf16 v[32:35], v[152:155], v[184:187], v[32:35]
	v_mfma_f32_16x16x32_bf16 v[28:31], v[160:163], v[184:187], v[28:31]
	v_mfma_f32_16x16x32_bf16 v[16:19], v[152:155], v[192:195], v[16:19]
	v_mfma_f32_16x16x32_bf16 v[12:15], v[160:163], v[192:195], v[12:15]
	s_setprio 0
	s_setprio 1
	v_mfma_f32_16x16x32_bf16 v[56:59], v[132:135], v[164:167], v[56:59]
	v_mfma_f32_16x16x32_bf16 v[52:55], v[140:143], v[164:167], v[52:55]
	v_mfma_f32_16x16x32_bf16 v[40:43], v[132:135], v[172:175], v[40:43]
	v_mfma_f32_16x16x32_bf16 v[36:39], v[140:143], v[172:175], v[36:39]
	v_mfma_f32_16x16x32_bf16 v[24:27], v[132:135], v[180:183], v[24:27]
	v_mfma_f32_16x16x32_bf16 v[20:23], v[140:143], v[180:183], v[20:23]
	v_mfma_f32_16x16x32_bf16 v[8:11], v[132:135], v[188:191], v[8:11]
	v_mfma_f32_16x16x32_bf16 v[2:5], v[140:143], v[188:191], v[4:7]
	v_mfma_f32_16x16x32_bf16 v[56:59], v[136:139], v[168:171], v[56:59]
	v_mfma_f32_16x16x32_bf16 v[52:55], v[144:147], v[168:171], v[52:55]
	v_mfma_f32_16x16x32_bf16 v[40:43], v[136:139], v[176:179], v[40:43]
	v_mfma_f32_16x16x32_bf16 v[36:39], v[144:147], v[176:179], v[36:39]
	v_mfma_f32_16x16x32_bf16 v[24:27], v[136:139], v[184:187], v[24:27]
	v_mfma_f32_16x16x32_bf16 v[20:23], v[144:147], v[184:187], v[20:23]
	v_mfma_f32_16x16x32_bf16 v[8:11], v[136:139], v[192:195], v[8:11]
	v_mfma_f32_16x16x32_bf16 v[2:5], v[144:147], v[192:195], v[2:5]
	s_setprio 0
	s_barrier
	v_add_u32_e32 v6, s75, v217
	ds_read_b128 v[148:151], v6
	ds_read_b128 v[152:155], v6 offset:1024
	ds_read_b128 v[156:159], v6 offset:2048
	ds_read_b128 v[160:163], v6 offset:3072
	v_add_u32_e32 v6, s76, v217
	ds_read_b128 v[132:135], v6
	ds_read_b128 v[136:139], v6 offset:1024
	ds_read_b128 v[140:143], v6 offset:2048
	ds_read_b128 v[144:147], v6 offset:3072
	s_cselect_b32 s45, s86, s84
	s_cselect_b32 s44, s85, s77
	s_mov_b32 m0, s52
	v_lshl_add_u64 v[6:7], s[44:45], 0, v[222:223]
	ds_read_b128 v[164:167], v219 offset:32768
	ds_read_b128 v[168:171], v219 offset:33792
	ds_read_b128 v[172:175], v219 offset:34816
	ds_read_b128 v[176:179], v219 offset:35840
	ds_read_b128 v[180:183], v219 offset:36864
	ds_read_b128 v[184:187], v219 offset:37888
	ds_read_b128 v[188:191], v219 offset:38912
	ds_read_b128 v[192:195], v219 offset:39936
	global_load_lds_dwordx4 v[6:7], off
	v_lshl_add_u64 v[6:7], s[44:45], 0, v[0:1]
	s_mov_b32 m0, s53
	s_nop 0
	global_load_lds_dwordx4 v[6:7], off
	s_waitcnt vmcnt(8)
	s_waitcnt lgkmcnt(0)
	s_barrier
	s_setprio 1
	v_mfma_f32_16x16x32_bf16 v[128:131], v[148:151], v[164:167], v[128:131]
	v_mfma_f32_16x16x32_bf16 v[124:127], v[156:159], v[164:167], v[124:127]
	v_mfma_f32_16x16x32_bf16 v[112:115], v[148:151], v[172:175], v[112:115]
	v_mfma_f32_16x16x32_bf16 v[108:111], v[156:159], v[172:175], v[108:111]
	v_mfma_f32_16x16x32_bf16 v[96:99], v[148:151], v[180:183], v[96:99]
	v_mfma_f32_16x16x32_bf16 v[92:95], v[156:159], v[180:183], v[92:95]
	v_mfma_f32_16x16x32_bf16 v[80:83], v[148:151], v[188:191], v[80:83]
	v_mfma_f32_16x16x32_bf16 v[76:79], v[156:159], v[188:191], v[76:79]
	v_mfma_f32_16x16x32_bf16 v[128:131], v[152:155], v[168:171], v[128:131]
	v_mfma_f32_16x16x32_bf16 v[124:127], v[160:163], v[168:171], v[124:127]
	v_mfma_f32_16x16x32_bf16 v[112:115], v[152:155], v[176:179], v[112:115]
	v_mfma_f32_16x16x32_bf16 v[108:111], v[160:163], v[176:179], v[108:111]
	v_mfma_f32_16x16x32_bf16 v[96:99], v[152:155], v[184:187], v[96:99]
	v_mfma_f32_16x16x32_bf16 v[92:95], v[160:163], v[184:187], v[92:95]
	v_mfma_f32_16x16x32_bf16 v[80:83], v[152:155], v[192:195], v[80:83]
	v_mfma_f32_16x16x32_bf16 v[76:79], v[160:163], v[192:195], v[76:79]
	s_setprio 0
	s_setprio 1
	v_mfma_f32_16x16x32_bf16 v[120:123], v[132:135], v[164:167], v[120:123]
	v_mfma_f32_16x16x32_bf16 v[116:119], v[140:143], v[164:167], v[116:119]
	v_mfma_f32_16x16x32_bf16 v[104:107], v[132:135], v[172:175], v[104:107]
	v_mfma_f32_16x16x32_bf16 v[100:103], v[140:143], v[172:175], v[100:103]
	v_mfma_f32_16x16x32_bf16 v[88:91], v[132:135], v[180:183], v[88:91]
	v_mfma_f32_16x16x32_bf16 v[84:87], v[140:143], v[180:183], v[84:87]
	v_mfma_f32_16x16x32_bf16 v[72:75], v[132:135], v[188:191], v[72:75]
	v_mfma_f32_16x16x32_bf16 v[68:71], v[140:143], v[188:191], v[68:71]
	v_mfma_f32_16x16x32_bf16 v[120:123], v[136:139], v[168:171], v[120:123]
	v_mfma_f32_16x16x32_bf16 v[116:119], v[144:147], v[168:171], v[116:119]
	v_mfma_f32_16x16x32_bf16 v[104:107], v[136:139], v[176:179], v[104:107]
	v_mfma_f32_16x16x32_bf16 v[100:103], v[144:147], v[176:179], v[100:103]
	v_mfma_f32_16x16x32_bf16 v[88:91], v[136:139], v[184:187], v[88:91]
	v_mfma_f32_16x16x32_bf16 v[84:87], v[144:147], v[184:187], v[84:87]
	v_mfma_f32_16x16x32_bf16 v[72:75], v[136:139], v[192:195], v[72:75]
	v_mfma_f32_16x16x32_bf16 v[68:71], v[144:147], v[192:195], v[68:71]
	s_setprio 0
	s_barrier
	s_add_i32 s44, s75, s33
	v_lshl_add_u64 v[6:7], v[214:215], 0, s[14:15]
	s_mov_b32 m0, s44
	ds_read_b128 v[188:191], v219 offset:49152
	ds_read_b128 v[192:195], v219 offset:50176
	ds_read_b128 v[180:183], v219 offset:51200
	ds_read_b128 v[184:187], v219 offset:52224
	ds_read_b128 v[172:175], v219 offset:53248
	ds_read_b128 v[176:179], v219 offset:54272
	ds_read_b128 v[164:167], v219 offset:55296
	ds_read_b128 v[168:171], v219 offset:56320
	global_load_lds_dwordx4 v[6:7], off
	s_add_i32 m0, s44, 0x2000
	s_add_u32 s42, s42, 0x80080
	v_lshl_add_u64 v[6:7], v[220:221], 0, s[14:15]
	s_addc_u32 s43, s43, 0
	s_add_i32 s44, s76, s33
	global_load_lds_dwordx4 v[6:7], off
	v_lshl_add_u64 v[6:7], s[42:43], 0, v[198:199]
	s_mov_b32 m0, s44
	s_add_i32 s70, s12, -7
	global_load_lds_dwordx4 v[6:7], off
	v_lshl_add_u64 v[6:7], s[42:43], 0, v[202:203]
	s_add_i32 m0, s44, 0x2000
	s_cmp_gt_u32 s70, 15
	global_load_lds_dwordx4 v[6:7], off
	s_mov_b64 s[44:45], -1
	s_cbranch_scc0 .LBB0_427
	s_or_b32 s12, s12, 1
	s_lshl_b64 s[42:43], s[12:13], 7
	s_add_u32 s42, s69, s42
	s_addc_u32 s43, s68, s43
	s_mov_b64 s[44:45], 0

.LBB0_429:
	s_mov_b32 m0, s55
	v_lshl_add_u64 v[214:215], s[42:43], 0, v[214:215]
	global_load_lds_dwordx4 v[214:215], off
	v_lshl_add_u64 v[6:7], s[42:43], 0, v[6:7]
	s_mov_b32 m0, s56
	s_nop 0
	global_load_lds_dwordx4 v[6:7], off
	s_waitcnt vmcnt(8)
	s_waitcnt lgkmcnt(0)
	s_barrier
	s_setprio 1
	v_mfma_f32_16x16x32_bf16 v[64:67], v[148:151], v[188:191], v[64:67]
	v_mfma_f32_16x16x32_bf16 v[60:63], v[156:159], v[188:191], v[60:63]
	v_mfma_f32_16x16x32_bf16 v[48:51], v[148:151], v[180:183], v[48:51]
	v_mfma_f32_16x16x32_bf16 v[44:47], v[156:159], v[180:183], v[44:47]
	v_mfma_f32_16x16x32_bf16 v[32:35], v[148:151], v[172:175], v[32:35]
	v_mfma_f32_16x16x32_bf16 v[28:31], v[156:159], v[172:175], v[28:31]
	v_mfma_f32_16x16x32_bf16 v[16:19], v[148:151], v[164:167], v[16:19]
	v_mfma_f32_16x16x32_bf16 v[12:15], v[156:159], v[164:167], v[12:15]
	v_mfma_f32_16x16x32_bf16 v[64:67], v[152:155], v[192:195], v[64:67]
	v_mfma_f32_16x16x32_bf16 v[60:63], v[160:163], v[192:195], v[60:63]
	v_mfma_f32_16x16x32_bf16 v[48:51], v[152:155], v[184:187], v[48:51]
	v_mfma_f32_16x16x32_bf16 v[44:47], v[160:163], v[184:187], v[44:47]
	v_mfma_f32_16x16x32_bf16 v[32:35], v[152:155], v[176:179], v[32:35]
	v_mfma_f32_16x16x32_bf16 v[28:31], v[160:163], v[176:179], v[28:31]
	v_mfma_f32_16x16x32_bf16 v[16:19], v[152:155], v[168:171], v[16:19]
	v_mfma_f32_16x16x32_bf16 v[12:15], v[160:163], v[168:171], v[12:15]
	s_setprio 0
	s_setprio 1
	v_mfma_f32_16x16x32_bf16 v[56:59], v[132:135], v[188:191], v[56:59]
	v_mfma_f32_16x16x32_bf16 v[52:55], v[140:143], v[188:191], v[52:55]
	v_mfma_f32_16x16x32_bf16 v[40:43], v[132:135], v[180:183], v[40:43]
	v_mfma_f32_16x16x32_bf16 v[36:39], v[140:143], v[180:183], v[36:39]
	v_mfma_f32_16x16x32_bf16 v[24:27], v[132:135], v[172:175], v[24:27]
	v_mfma_f32_16x16x32_bf16 v[20:23], v[140:143], v[172:175], v[20:23]
	v_mfma_f32_16x16x32_bf16 v[6:9], v[132:135], v[164:167], v[8:11]
	v_mfma_f32_16x16x32_bf16 v[2:5], v[140:143], v[164:167], v[2:5]
	v_mfma_f32_16x16x32_bf16 v[56:59], v[136:139], v[192:195], v[56:59]
	v_mfma_f32_16x16x32_bf16 v[52:55], v[144:147], v[192:195], v[52:55]
	v_mfma_f32_16x16x32_bf16 v[40:43], v[136:139], v[184:187], v[40:43]
	v_mfma_f32_16x16x32_bf16 v[36:39], v[144:147], v[184:187], v[36:39]
	v_mfma_f32_16x16x32_bf16 v[24:27], v[136:139], v[176:179], v[24:27]
	v_mfma_f32_16x16x32_bf16 v[20:23], v[144:147], v[176:179], v[20:23]
	v_mfma_f32_16x16x32_bf16 v[8:11], v[136:139], v[168:171], v[6:9]
	v_mfma_f32_16x16x32_bf16 v[4:7], v[144:147], v[168:171], v[2:5]
	s_setprio 0
	s_barrier
	s_add_u32 s38, s38, 0x100
	s_addc_u32 s39, s39, 0
	s_add_i32 s63, s63, 0x100000
	s_cmp_gt_u32 s64, 29
	s_cbranch_scc1 .LBB0_408
	s_mov_b32 s64, s65
	s_cmp_lt_i32 s64, 24
	s_cbranch_scc1 .LBB0_417
	s_branch .LBB0_416

.LBB0_504:
	s_add_u32 s20, s31, s44
	ds_read_b128 v[132:135], v217
	ds_read_b128 v[136:139], v217 offset:1024
	ds_read_b128 v[140:143], v217 offset:2048
	ds_read_b128 v[144:147], v217 offset:3072
	ds_read_b128 v[148:151], v218
	ds_read_b128 v[152:155], v218 offset:1024
	ds_read_b128 v[156:159], v218 offset:2048
	ds_read_b128 v[160:163], v218 offset:3072
	s_addc_u32 s48, s39, s45
	s_cmpk_eq_i32 s44, 0x700
	s_cselect_b64 s[46:47], -1, 0
	s_and_b64 s[46:47], s[46:47], exec
	s_cselect_b32 s47, s19, s48
	s_cselect_b32 s46, s29, s20
	s_add_i32 s64, s63, 2
	s_cmpk_eq_i32 s44, 0x700
	s_cselect_b64 s[48:49], -1, 0
	s_and_b64 s[66:67], s[48:49], exec
	s_cselect_b32 s20, 0, s64
	s_and_b64 s[48:49], s[48:49], s[6:7]
	s_and_b64 s[48:49], s[48:49], exec
	s_cselect_b32 s48, s35, s43
	s_cselect_b32 s49, s34, s42
	v_lshl_add_u64 v[238:239], v[128:129], 0, s[44:45]
	s_add_i32 m0, s50, 0xc000
	ds_read_b128 v[164:167], v219
	ds_read_b128 v[168:171], v219 offset:1024
	ds_read_b128 v[172:175], v219 offset:2048
	ds_read_b128 v[192:195], v219 offset:3072
	ds_read_b128 v[222:225], v219 offset:4096
	ds_read_b128 v[226:229], v219 offset:5120
	ds_read_b128 v[230:233], v219 offset:6144
	ds_read_b128 v[234:237], v219 offset:7168
	global_load_lds_dwordx4 v[238:239], off
	v_lshl_add_u64 v[238:239], v[130:131], 0, s[44:45]
	s_add_i32 m0, s50, 0xe000
	s_nop 0
	global_load_lds_dwordx4 v[238:239], off
	s_waitcnt vmcnt(8)
	s_waitcnt lgkmcnt(0)
	s_barrier
	s_setprio 1
	v_mfma_f32_16x16x32_bf16 v[124:127], v[132:135], v[164:167], v[124:127]
	v_mfma_f32_16x16x32_bf16 v[120:123], v[140:143], v[164:167], v[120:123]
	v_mfma_f32_16x16x32_bf16 v[108:111], v[132:135], v[172:175], v[108:111]
	v_mfma_f32_16x16x32_bf16 v[104:107], v[140:143], v[172:175], v[104:107]
	v_mfma_f32_16x16x32_bf16 v[92:95], v[132:135], v[222:225], v[92:95]
	v_mfma_f32_16x16x32_bf16 v[88:91], v[140:143], v[222:225], v[88:91]
	v_mfma_f32_16x16x32_bf16 v[76:79], v[132:135], v[230:233], v[76:79]
	v_mfma_f32_16x16x32_bf16 v[72:75], v[140:143], v[230:233], v[72:75]
	v_mfma_f32_16x16x32_bf16 v[124:127], v[136:139], v[168:171], v[124:127]
	v_mfma_f32_16x16x32_bf16 v[120:123], v[144:147], v[168:171], v[120:123]
	v_mfma_f32_16x16x32_bf16 v[108:111], v[136:139], v[192:195], v[108:111]
	v_mfma_f32_16x16x32_bf16 v[104:107], v[144:147], v[192:195], v[104:107]
	v_mfma_f32_16x16x32_bf16 v[92:95], v[136:139], v[226:229], v[92:95]
	v_mfma_f32_16x16x32_bf16 v[88:91], v[144:147], v[226:229], v[88:91]
	v_mfma_f32_16x16x32_bf16 v[76:79], v[136:139], v[234:237], v[76:79]
	v_mfma_f32_16x16x32_bf16 v[72:75], v[144:147], v[234:237], v[72:75]
	s_setprio 0
	s_setprio 1
	v_mfma_f32_16x16x32_bf16 v[116:119], v[148:151], v[164:167], v[116:119]
	v_mfma_f32_16x16x32_bf16 v[112:115], v[156:159], v[164:167], v[112:115]
	v_mfma_f32_16x16x32_bf16 v[100:103], v[148:151], v[172:175], v[100:103]
	v_mfma_f32_16x16x32_bf16 v[96:99], v[156:159], v[172:175], v[96:99]
	v_mfma_f32_16x16x32_bf16 v[84:87], v[148:151], v[222:225], v[84:87]
	v_mfma_f32_16x16x32_bf16 v[80:83], v[156:159], v[222:225], v[80:83]
	v_mfma_f32_16x16x32_bf16 v[68:71], v[148:151], v[230:233], v[68:71]
	v_mfma_f32_16x16x32_bf16 v[64:67], v[156:159], v[230:233], v[64:67]
	v_mfma_f32_16x16x32_bf16 v[116:119], v[152:155], v[168:171], v[116:119]
	v_mfma_f32_16x16x32_bf16 v[112:115], v[160:163], v[168:171], v[112:115]
	v_mfma_f32_16x16x32_bf16 v[100:103], v[152:155], v[192:195], v[100:103]
	v_mfma_f32_16x16x32_bf16 v[96:99], v[160:163], v[192:195], v[96:99]
	v_mfma_f32_16x16x32_bf16 v[84:87], v[152:155], v[226:229], v[84:87]
	v_mfma_f32_16x16x32_bf16 v[80:83], v[160:163], v[226:229], v[80:83]
	v_mfma_f32_16x16x32_bf16 v[68:71], v[152:155], v[234:237], v[68:71]
	v_mfma_f32_16x16x32_bf16 v[64:67], v[160:163], v[234:237], v[64:67]
	s_setprio 0
	s_barrier
	s_add_i32 s65, s58, s33
	v_lshl_add_u64 v[238:239], s[46:47], 0, v[178:179]
	s_mov_b32 m0, s65
	ds_read_b128 v[164:167], v219 offset:16384
	ds_read_b128 v[168:171], v219 offset:17408
	ds_read_b128 v[172:175], v219 offset:18432
	ds_read_b128 v[192:195], v219 offset:19456
	ds_read_b128 v[222:225], v219 offset:20480
	ds_read_b128 v[226:229], v219 offset:21504
	ds_read_b128 v[230:233], v219 offset:22528
	ds_read_b128 v[234:237], v219 offset:23552
	global_load_lds_dwordx4 v[238:239], off
	s_add_i32 m0, s65, 0x2000
	s_add_u32 s66, s46, 0x40000
	v_lshl_add_u64 v[240:241], s[46:47], 0, v[182:183]
	s_addc_u32 s67, s47, 0
	s_add_i32 s65, s59, s33
	global_load_lds_dwordx4 v[240:241], off
	v_lshl_add_u64 v[242:243], s[66:67], 0, v[178:179]
	s_mov_b32 m0, s65
	s_nop 0
	global_load_lds_dwordx4 v[242:243], off
	v_lshl_add_u64 v[242:243], s[66:67], 0, v[182:183]
	s_add_i32 m0, s65, 0x2000
	s_lshl_b64 s[66:67], s[20:21], 7
	s_add_u32 s66, s49, s66
	s_addc_u32 s67, s48, s67
	global_load_lds_dwordx4 v[242:243], off
	v_lshl_add_u64 v[242:243], s[66:67], 0, v[176:177]
	s_mov_b32 m0, s50
	s_nop 0
	global_load_lds_dwordx4 v[242:243], off
	v_lshl_add_u64 v[242:243], s[66:67], 0, v[180:181]
	s_mov_b32 m0, s51
	s_nop 0
	global_load_lds_dwordx4 v[242:243], off
	s_waitcnt vmcnt(8)
	s_waitcnt lgkmcnt(0)
	s_barrier
	s_setprio 1
	v_mfma_f32_16x16x32_bf16 v[60:63], v[132:135], v[164:167], v[60:63]
	v_mfma_f32_16x16x32_bf16 v[56:59], v[140:143], v[164:167], v[56:59]
	v_mfma_f32_16x16x32_bf16 v[44:47], v[132:135], v[172:175], v[44:47]
	v_mfma_f32_16x16x32_bf16 v[40:43], v[140:143], v[172:175], v[40:43]
	v_mfma_f32_16x16x32_bf16 v[28:31], v[132:135], v[222:225], v[28:31]
	v_mfma_f32_16x16x32_bf16 v[24:27], v[140:143], v[222:225], v[24:27]
	v_mfma_f32_16x16x32_bf16 v[12:15], v[132:135], v[230:233], v[12:15]
	v_mfma_f32_16x16x32_bf16 v[8:11], v[140:143], v[230:233], v[8:11]
	v_mfma_f32_16x16x32_bf16 v[60:63], v[136:139], v[168:171], v[60:63]
	v_mfma_f32_16x16x32_bf16 v[56:59], v[144:147], v[168:171], v[56:59]
	v_mfma_f32_16x16x32_bf16 v[44:47], v[136:139], v[192:195], v[44:47]
	v_mfma_f32_16x16x32_bf16 v[40:43], v[144:147], v[192:195], v[40:43]
	v_mfma_f32_16x16x32_bf16 v[28:31], v[136:139], v[226:229], v[28:31]
	v_mfma_f32_16x16x32_bf16 v[24:27], v[144:147], v[226:229], v[24:27]
	v_mfma_f32_16x16x32_bf16 v[12:15], v[136:139], v[234:237], v[12:15]
	v_mfma_f32_16x16x32_bf16 v[8:11], v[144:147], v[234:237], v[8:11]
	s_setprio 0
	s_setprio 1
	v_mfma_f32_16x16x32_bf16 v[52:55], v[148:151], v[164:167], v[52:55]
	v_mfma_f32_16x16x32_bf16 v[48:51], v[156:159], v[164:167], v[48:51]
	v_mfma_f32_16x16x32_bf16 v[36:39], v[148:151], v[172:175], v[36:39]
	v_mfma_f32_16x16x32_bf16 v[32:35], v[156:159], v[172:175], v[32:35]
	v_mfma_f32_16x16x32_bf16 v[20:23], v[148:151], v[222:225], v[20:23]
	v_mfma_f32_16x16x32_bf16 v[16:19], v[156:159], v[222:225], v[16:19]
	v_mfma_f32_16x16x32_bf16 v[4:7], v[148:151], v[230:233], v[4:7]
	v_mfma_f32_16x16x32_bf16 v[0:3], v[156:159], v[230:233], v[0:3]
	v_mfma_f32_16x16x32_bf16 v[52:55], v[152:155], v[168:171], v[52:55]
	v_mfma_f32_16x16x32_bf16 v[48:51], v[160:163], v[168:171], v[48:51]
	v_mfma_f32_16x16x32_bf16 v[36:39], v[152:155], v[192:195], v[36:39]
	v_mfma_f32_16x16x32_bf16 v[32:35], v[160:163], v[192:195], v[32:35]
	v_mfma_f32_16x16x32_bf16 v[20:23], v[152:155], v[226:229], v[20:23]
	v_mfma_f32_16x16x32_bf16 v[16:19], v[160:163], v[226:229], v[16:19]
	v_mfma_f32_16x16x32_bf16 v[4:7], v[152:155], v[234:237], v[4:7]
	v_mfma_f32_16x16x32_bf16 v[0:3], v[160:163], v[234:237], v[0:3]
	s_setprio 0
	s_barrier
	s_add_i32 s65, 0, 0x18000
	s_add_i32 s68, 0, 0x1c000
	v_add_u32_e32 v144, s65, v198
	v_add_u32_e32 v160, s68, v198
	ds_read_b128 v[132:135], v144
	ds_read_b128 v[136:139], v144 offset:1024
	ds_read_b128 v[140:143], v144 offset:2048
	ds_read_b128 v[144:147], v144 offset:3072
	ds_read_b128 v[148:151], v160
	ds_read_b128 v[152:155], v160 offset:1024
	ds_read_b128 v[156:159], v160 offset:2048
	ds_read_b128 v[160:163], v160 offset:3072
	s_add_u32 s66, s66, 0x40000
	s_addc_u32 s67, s67, 0
	s_mov_b32 m0, s52
	v_lshl_add_u64 v[242:243], s[66:67], 0, v[176:177]
	ds_read_b128 v[164:167], v219 offset:32768
	ds_read_b128 v[168:171], v219 offset:33792
	ds_read_b128 v[172:175], v219 offset:34816
	ds_read_b128 v[192:195], v219 offset:35840
	ds_read_b128 v[222:225], v219 offset:36864
	ds_read_b128 v[226:229], v219 offset:37888
	ds_read_b128 v[230:233], v219 offset:38912
	ds_read_b128 v[234:237], v219 offset:39936
	global_load_lds_dwordx4 v[242:243], off
	v_lshl_add_u64 v[242:243], s[66:67], 0, v[180:181]
	s_mov_b32 m0, s53
	s_nop 0
	global_load_lds_dwordx4 v[242:243], off
	s_waitcnt vmcnt(8)
	s_waitcnt lgkmcnt(0)
	s_barrier
	s_setprio 1
	v_mfma_f32_16x16x32_bf16 v[124:127], v[132:135], v[164:167], v[124:127]
	v_mfma_f32_16x16x32_bf16 v[120:123], v[140:143], v[164:167], v[120:123]
	v_mfma_f32_16x16x32_bf16 v[108:111], v[132:135], v[172:175], v[108:111]
	v_mfma_f32_16x16x32_bf16 v[104:107], v[140:143], v[172:175], v[104:107]
	v_mfma_f32_16x16x32_bf16 v[92:95], v[132:135], v[222:225], v[92:95]
	v_mfma_f32_16x16x32_bf16 v[88:91], v[140:143], v[222:225], v[88:91]
	v_mfma_f32_16x16x32_bf16 v[76:79], v[132:135], v[230:233], v[76:79]
	v_mfma_f32_16x16x32_bf16 v[72:75], v[140:143], v[230:233], v[72:75]
	v_mfma_f32_16x16x32_bf16 v[124:127], v[136:139], v[168:171], v[124:127]
	v_mfma_f32_16x16x32_bf16 v[120:123], v[144:147], v[168:171], v[120:123]
	v_mfma_f32_16x16x32_bf16 v[108:111], v[136:139], v[192:195], v[108:111]
	v_mfma_f32_16x16x32_bf16 v[104:107], v[144:147], v[192:195], v[104:107]
	v_mfma_f32_16x16x32_bf16 v[92:95], v[136:139], v[226:229], v[92:95]
	v_mfma_f32_16x16x32_bf16 v[88:91], v[144:147], v[226:229], v[88:91]
	v_mfma_f32_16x16x32_bf16 v[76:79], v[136:139], v[234:237], v[76:79]
	v_mfma_f32_16x16x32_bf16 v[72:75], v[144:147], v[234:237], v[72:75]
	s_setprio 0
	s_setprio 1
	v_mfma_f32_16x16x32_bf16 v[116:119], v[148:151], v[164:167], v[116:119]
	v_mfma_f32_16x16x32_bf16 v[112:115], v[156:159], v[164:167], v[112:115]
	v_mfma_f32_16x16x32_bf16 v[100:103], v[148:151], v[172:175], v[100:103]
	v_mfma_f32_16x16x32_bf16 v[96:99], v[156:159], v[172:175], v[96:99]
	v_mfma_f32_16x16x32_bf16 v[84:87], v[148:151], v[222:225], v[84:87]
	v_mfma_f32_16x16x32_bf16 v[80:83], v[156:159], v[222:225], v[80:83]
	v_mfma_f32_16x16x32_bf16 v[68:71], v[148:151], v[230:233], v[68:71]
	v_mfma_f32_16x16x32_bf16 v[64:67], v[156:159], v[230:233], v[64:67]
	v_mfma_f32_16x16x32_bf16 v[116:119], v[152:155], v[168:171], v[116:119]
	v_mfma_f32_16x16x32_bf16 v[112:115], v[160:163], v[168:171], v[112:115]
	v_mfma_f32_16x16x32_bf16 v[100:103], v[152:155], v[192:195], v[100:103]
	v_mfma_f32_16x16x32_bf16 v[96:99], v[160:163], v[192:195], v[96:99]
	v_mfma_f32_16x16x32_bf16 v[84:87], v[152:155], v[226:229], v[84:87]
	v_mfma_f32_16x16x32_bf16 v[80:83], v[160:163], v[226:229], v[80:83]
	v_mfma_f32_16x16x32_bf16 v[68:71], v[152:155], v[234:237], v[68:71]
	v_mfma_f32_16x16x32_bf16 v[64:67], v[160:163], v[234:237], v[64:67]
	s_setprio 0
	s_barrier
	s_add_i32 s65, s65, s33
	v_lshl_add_u64 v[238:239], v[238:239], 0, s[24:25]
	s_mov_b32 m0, s65
	ds_read_b128 v[164:167], v219 offset:49152
	ds_read_b128 v[168:171], v219 offset:50176
	ds_read_b128 v[172:175], v219 offset:51200
	ds_read_b128 v[192:195], v219 offset:52224
	ds_read_b128 v[222:225], v219 offset:53248
	ds_read_b128 v[226:229], v219 offset:54272
	ds_read_b128 v[230:233], v219 offset:55296
	ds_read_b128 v[234:237], v219 offset:56320
	global_load_lds_dwordx4 v[238:239], off
	s_add_i32 m0, s65, 0x2000
	s_add_u32 s46, s46, 0x40080
	v_lshl_add_u64 v[238:239], v[240:241], 0, s[24:25]
	s_addc_u32 s47, s47, 0
	s_add_i32 s65, s68, s33
	global_load_lds_dwordx4 v[238:239], off
	v_lshl_add_u64 v[238:239], s[46:47], 0, v[178:179]
	s_mov_b32 m0, s65
	s_or_b32 s20, s20, 1
	global_load_lds_dwordx4 v[238:239], off
	v_lshl_add_u64 v[238:239], s[46:47], 0, v[182:183]
	s_add_i32 m0, s65, 0x2000
	s_lshl_b64 s[46:47], s[20:21], 7
	s_add_u32 s46, s49, s46
	s_addc_u32 s47, s48, s47
	global_load_lds_dwordx4 v[238:239], off
	v_lshl_add_u64 v[238:239], s[46:47], 0, v[176:177]
	s_mov_b32 m0, s56
	s_nop 0
	global_load_lds_dwordx4 v[238:239], off
	v_lshl_add_u64 v[238:239], s[46:47], 0, v[180:181]
	s_mov_b32 m0, s57
	s_nop 0
	global_load_lds_dwordx4 v[238:239], off
	s_waitcnt vmcnt(8)
	s_waitcnt lgkmcnt(0)
	s_barrier
	s_setprio 1
	v_mfma_f32_16x16x32_bf16 v[60:63], v[132:135], v[164:167], v[60:63]
	v_mfma_f32_16x16x32_bf16 v[56:59], v[140:143], v[164:167], v[56:59]
	v_mfma_f32_16x16x32_bf16 v[44:47], v[132:135], v[172:175], v[44:47]
	v_mfma_f32_16x16x32_bf16 v[40:43], v[140:143], v[172:175], v[40:43]
	v_mfma_f32_16x16x32_bf16 v[28:31], v[132:135], v[222:225], v[28:31]
	v_mfma_f32_16x16x32_bf16 v[24:27], v[140:143], v[222:225], v[24:27]
	v_mfma_f32_16x16x32_bf16 v[12:15], v[132:135], v[230:233], v[12:15]
	v_mfma_f32_16x16x32_bf16 v[8:11], v[140:143], v[230:233], v[8:11]
	v_mfma_f32_16x16x32_bf16 v[60:63], v[136:139], v[168:171], v[60:63]
	v_mfma_f32_16x16x32_bf16 v[56:59], v[144:147], v[168:171], v[56:59]
	v_mfma_f32_16x16x32_bf16 v[44:47], v[136:139], v[192:195], v[44:47]
	v_mfma_f32_16x16x32_bf16 v[40:43], v[144:147], v[192:195], v[40:43]
	v_mfma_f32_16x16x32_bf16 v[28:31], v[136:139], v[226:229], v[28:31]
	v_mfma_f32_16x16x32_bf16 v[24:27], v[144:147], v[226:229], v[24:27]
	v_mfma_f32_16x16x32_bf16 v[12:15], v[136:139], v[234:237], v[12:15]
	v_mfma_f32_16x16x32_bf16 v[8:11], v[144:147], v[234:237], v[8:11]
	s_setprio 0
	s_setprio 1
	v_mfma_f32_16x16x32_bf16 v[52:55], v[148:151], v[164:167], v[52:55]
	v_mfma_f32_16x16x32_bf16 v[48:51], v[156:159], v[164:167], v[48:51]
	v_mfma_f32_16x16x32_bf16 v[36:39], v[148:151], v[172:175], v[36:39]
	v_mfma_f32_16x16x32_bf16 v[32:35], v[156:159], v[172:175], v[32:35]
	v_mfma_f32_16x16x32_bf16 v[20:23], v[148:151], v[222:225], v[20:23]
	v_mfma_f32_16x16x32_bf16 v[16:19], v[156:159], v[222:225], v[16:19]
	v_mfma_f32_16x16x32_bf16 v[4:7], v[148:151], v[230:233], v[4:7]
	v_mfma_f32_16x16x32_bf16 v[0:3], v[156:159], v[230:233], v[0:3]
	v_mfma_f32_16x16x32_bf16 v[52:55], v[152:155], v[168:171], v[52:55]
	v_mfma_f32_16x16x32_bf16 v[48:51], v[160:163], v[168:171], v[48:51]
	v_mfma_f32_16x16x32_bf16 v[36:39], v[152:155], v[192:195], v[36:39]
	v_mfma_f32_16x16x32_bf16 v[32:35], v[160:163], v[192:195], v[32:35]
	v_mfma_f32_16x16x32_bf16 v[20:23], v[152:155], v[226:229], v[20:23]
	v_mfma_f32_16x16x32_bf16 v[16:19], v[160:163], v[226:229], v[16:19]
	v_mfma_f32_16x16x32_bf16 v[4:7], v[152:155], v[234:237], v[4:7]
	v_mfma_f32_16x16x32_bf16 v[0:3], v[160:163], v[234:237], v[0:3]
	s_setprio 0
	s_barrier
	s_add_u32 s44, s44, 0x100
	s_addc_u32 s45, s45, 0
	s_cmp_gt_u32 s63, 13
	s_mov_b32 s63, s64
	s_cbranch_scc0 .LBB0_504
	s_and_b64 vcc, exec, s[26:27]
	s_cbranch_vccz .LBB0_507
	s_barrier

.LBB0_599:
	s_add_u32 s16, s57, s38
	ds_read_b128 v[178:181], v173
	ds_read_b128 v[182:185], v173 offset:1024
	ds_read_b128 v[186:189], v173 offset:2048
	ds_read_b128 v[190:193], v173 offset:3072
	ds_read_b128 v[194:197], v174
	ds_read_b128 v[198:201], v174 offset:1024
	ds_read_b128 v[202:205], v174 offset:2048
	ds_read_b128 v[206:209], v174 offset:3072
	s_addc_u32 s42, s58, s39
	s_cmpk_eq_i32 s38, 0x700
	s_cselect_b64 s[40:41], -1, 0
	s_and_b64 s[40:41], s[40:41], exec
	s_cselect_b32 s41, s25, s42
	s_cselect_b32 s40, s27, s16
	s_add_i32 s60, s59, 2
	s_cmpk_eq_i32 s38, 0x700
	s_cselect_b64 s[42:43], -1, 0
	s_and_b64 s[62:63], s[42:43], exec
	s_cselect_b32 s16, 0, s60
	s_and_b64 s[42:43], s[42:43], s[4:5]
	s_and_b64 s[42:43], s[42:43], exec
	s_cselect_b32 s42, s29, s37
	s_cselect_b32 s43, s28, s36
	v_lshl_add_u64 v[214:215], v[144:145], 0, s[38:39]
	s_add_i32 m0, s35, 0xc000
	ds_read_b128 v[210:213], v175
	ds_read_b128 v[218:221], v175 offset:1024
	ds_read_b128 v[222:225], v175 offset:2048
	ds_read_b128 v[226:229], v175 offset:3072
	ds_read_b128 v[230:233], v175 offset:4096
	ds_read_b128 v[234:237], v175 offset:5120
	ds_read_b128 v[238:241], v175 offset:6144
	ds_read_b128 v[242:245], v175 offset:7168
	global_load_lds_dwordx4 v[214:215], off
	v_lshl_add_u64 v[214:215], v[146:147], 0, s[38:39]
	s_add_i32 m0, s35, 0xe000
	s_nop 0
	global_load_lds_dwordx4 v[214:215], off
	s_waitcnt vmcnt(8)
	s_waitcnt lgkmcnt(0)
	s_barrier
	s_setprio 1
	v_mfma_f32_16x16x32_bf16 v[124:127], v[178:181], v[210:213], v[124:127]
	v_mfma_f32_16x16x32_bf16 v[120:123], v[186:189], v[210:213], v[120:123]
	v_mfma_f32_16x16x32_bf16 v[116:119], v[178:181], v[222:225], v[116:119]
	v_mfma_f32_16x16x32_bf16 v[108:111], v[186:189], v[222:225], v[108:111]
	v_mfma_f32_16x16x32_bf16 v[100:103], v[178:181], v[230:233], v[100:103]
	v_mfma_f32_16x16x32_bf16 v[92:95], v[186:189], v[230:233], v[92:95]
	v_mfma_f32_16x16x32_bf16 v[84:87], v[178:181], v[238:241], v[84:87]
	v_mfma_f32_16x16x32_bf16 v[76:79], v[186:189], v[238:241], v[76:79]
	v_mfma_f32_16x16x32_bf16 v[124:127], v[182:185], v[218:221], v[124:127]
	v_mfma_f32_16x16x32_bf16 v[120:123], v[190:193], v[218:221], v[120:123]
	v_mfma_f32_16x16x32_bf16 v[116:119], v[182:185], v[226:229], v[116:119]
	v_mfma_f32_16x16x32_bf16 v[108:111], v[190:193], v[226:229], v[108:111]
	v_mfma_f32_16x16x32_bf16 v[100:103], v[182:185], v[234:237], v[100:103]
	v_mfma_f32_16x16x32_bf16 v[92:95], v[190:193], v[234:237], v[92:95]
	v_mfma_f32_16x16x32_bf16 v[84:87], v[182:185], v[242:245], v[84:87]
	v_mfma_f32_16x16x32_bf16 v[76:79], v[190:193], v[242:245], v[76:79]
	s_setprio 0
	s_setprio 1
	v_mfma_f32_16x16x32_bf16 v[112:115], v[194:197], v[210:213], v[112:115]
	v_mfma_f32_16x16x32_bf16 v[104:107], v[202:205], v[210:213], v[104:107]
	v_mfma_f32_16x16x32_bf16 v[96:99], v[194:197], v[222:225], v[96:99]
	v_mfma_f32_16x16x32_bf16 v[88:91], v[202:205], v[222:225], v[88:91]
	v_mfma_f32_16x16x32_bf16 v[80:83], v[194:197], v[230:233], v[80:83]
	v_mfma_f32_16x16x32_bf16 v[72:75], v[202:205], v[230:233], v[72:75]
	v_mfma_f32_16x16x32_bf16 v[68:71], v[194:197], v[238:241], v[68:71]
	v_mfma_f32_16x16x32_bf16 v[64:67], v[202:205], v[238:241], v[64:67]
	v_mfma_f32_16x16x32_bf16 v[112:115], v[198:201], v[218:221], v[112:115]
	v_mfma_f32_16x16x32_bf16 v[104:107], v[206:209], v[218:221], v[104:107]
	v_mfma_f32_16x16x32_bf16 v[96:99], v[198:201], v[226:229], v[96:99]
	v_mfma_f32_16x16x32_bf16 v[88:91], v[206:209], v[226:229], v[88:91]
	v_mfma_f32_16x16x32_bf16 v[80:83], v[198:201], v[234:237], v[80:83]
	v_mfma_f32_16x16x32_bf16 v[72:75], v[206:209], v[234:237], v[72:75]
	v_mfma_f32_16x16x32_bf16 v[68:71], v[198:201], v[242:245], v[68:71]
	v_mfma_f32_16x16x32_bf16 v[64:67], v[206:209], v[242:245], v[64:67]
	s_setprio 0
	s_barrier
	s_add_i32 s61, s51, s33
	v_lshl_add_u64 v[214:215], s[40:41], 0, v[130:131]
	s_mov_b32 m0, s61
	ds_read_b128 v[210:213], v175 offset:16384
	ds_read_b128 v[218:221], v175 offset:17408
	ds_read_b128 v[222:225], v175 offset:18432
	ds_read_b128 v[226:229], v175 offset:19456
	ds_read_b128 v[230:233], v175 offset:20480
	ds_read_b128 v[234:237], v175 offset:21504
	ds_read_b128 v[238:241], v175 offset:22528
	ds_read_b128 v[242:245], v175 offset:23552
	global_load_lds_dwordx4 v[214:215], off
	s_add_i32 m0, s61, 0x2000
	s_add_u32 s62, s40, 0x40000
	v_lshl_add_u64 v[246:247], s[40:41], 0, v[134:135]
	s_addc_u32 s63, s41, 0
	s_add_i32 s61, s52, s33
	global_load_lds_dwordx4 v[246:247], off
	v_lshl_add_u64 v[248:249], s[62:63], 0, v[130:131]
	s_mov_b32 m0, s61
	s_nop 0
	global_load_lds_dwordx4 v[248:249], off
	v_lshl_add_u64 v[248:249], s[62:63], 0, v[134:135]
	s_add_i32 m0, s61, 0x2000
	s_lshl_b64 s[62:63], s[16:17], 7
	s_add_u32 s62, s43, s62
	s_addc_u32 s63, s42, s63
	global_load_lds_dwordx4 v[248:249], off
	v_lshl_add_u64 v[248:249], s[62:63], 0, v[128:129]
	s_mov_b32 m0, s35
	s_nop 0
	global_load_lds_dwordx4 v[248:249], off
	v_lshl_add_u64 v[248:249], s[62:63], 0, v[132:133]
	s_mov_b32 m0, s45
	s_nop 0
	global_load_lds_dwordx4 v[248:249], off
	s_waitcnt vmcnt(8)
	s_waitcnt lgkmcnt(0)
	s_barrier
	s_setprio 1
	v_mfma_f32_16x16x32_bf16 v[60:63], v[178:181], v[210:213], v[60:63]
	v_mfma_f32_16x16x32_bf16 v[56:59], v[186:189], v[210:213], v[56:59]
	v_mfma_f32_16x16x32_bf16 v[52:55], v[178:181], v[222:225], v[52:55]
	v_mfma_f32_16x16x32_bf16 v[44:47], v[186:189], v[222:225], v[44:47]
	v_mfma_f32_16x16x32_bf16 v[36:39], v[178:181], v[230:233], v[36:39]
	v_mfma_f32_16x16x32_bf16 v[28:31], v[186:189], v[230:233], v[28:31]
	v_mfma_f32_16x16x32_bf16 v[16:19], v[178:181], v[238:241], v[16:19]
	v_mfma_f32_16x16x32_bf16 v[8:11], v[186:189], v[238:241], v[8:11]
	v_mfma_f32_16x16x32_bf16 v[60:63], v[182:185], v[218:221], v[60:63]
	v_mfma_f32_16x16x32_bf16 v[56:59], v[190:193], v[218:221], v[56:59]
	v_mfma_f32_16x16x32_bf16 v[52:55], v[182:185], v[226:229], v[52:55]
	v_mfma_f32_16x16x32_bf16 v[44:47], v[190:193], v[226:229], v[44:47]
	v_mfma_f32_16x16x32_bf16 v[36:39], v[182:185], v[234:237], v[36:39]
	v_mfma_f32_16x16x32_bf16 v[28:31], v[190:193], v[234:237], v[28:31]
	v_mfma_f32_16x16x32_bf16 v[16:19], v[182:185], v[242:245], v[16:19]
	v_mfma_f32_16x16x32_bf16 v[8:11], v[190:193], v[242:245], v[8:11]
	s_setprio 0
	s_setprio 1
	v_mfma_f32_16x16x32_bf16 v[48:51], v[194:197], v[210:213], v[48:51]
	v_mfma_f32_16x16x32_bf16 v[40:43], v[202:205], v[210:213], v[40:43]
	v_mfma_f32_16x16x32_bf16 v[32:35], v[194:197], v[222:225], v[32:35]
	v_mfma_f32_16x16x32_bf16 v[24:27], v[202:205], v[222:225], v[24:27]
	v_mfma_f32_16x16x32_bf16 v[20:23], v[194:197], v[230:233], v[20:23]
	v_mfma_f32_16x16x32_bf16 v[12:15], v[202:205], v[230:233], v[12:15]
	v_mfma_f32_16x16x32_bf16 v[4:7], v[194:197], v[238:241], v[4:7]
	v_mfma_f32_16x16x32_bf16 v[0:3], v[202:205], v[238:241], v[0:3]
	v_mfma_f32_16x16x32_bf16 v[48:51], v[198:201], v[218:221], v[48:51]
	v_mfma_f32_16x16x32_bf16 v[40:43], v[206:209], v[218:221], v[40:43]
	v_mfma_f32_16x16x32_bf16 v[32:35], v[198:201], v[226:229], v[32:35]
	v_mfma_f32_16x16x32_bf16 v[24:27], v[206:209], v[226:229], v[24:27]
	v_mfma_f32_16x16x32_bf16 v[20:23], v[198:201], v[234:237], v[20:23]
	v_mfma_f32_16x16x32_bf16 v[12:15], v[206:209], v[234:237], v[12:15]
	v_mfma_f32_16x16x32_bf16 v[4:7], v[198:201], v[242:245], v[4:7]
	v_mfma_f32_16x16x32_bf16 v[0:3], v[206:209], v[242:245], v[0:3]
	s_setprio 0
	s_barrier
	s_add_i32 s61, 0, 0x18000
	v_add_u32_e32 v148, s61, v151
	s_add_i32 s64, 0, 0x1c000
	ds_read_b128 v[178:181], v148
	ds_read_b128 v[182:185], v148 offset:1024
	ds_read_b128 v[186:189], v148 offset:2048
	ds_read_b128 v[190:193], v148 offset:3072
	v_add_u32_e32 v148, s64, v151
	ds_read_b128 v[194:197], v148
	ds_read_b128 v[198:201], v148 offset:1024
	ds_read_b128 v[202:205], v148 offset:2048
	ds_read_b128 v[206:209], v148 offset:3072
	s_add_u32 s62, s62, 0x40000
	s_addc_u32 s63, s63, 0
	s_mov_b32 m0, s46
	v_lshl_add_u64 v[248:249], s[62:63], 0, v[128:129]
	ds_read_b128 v[210:213], v175 offset:32768
	ds_read_b128 v[218:221], v175 offset:33792
	ds_read_b128 v[222:225], v175 offset:34816
	ds_read_b128 v[226:229], v175 offset:35840
	ds_read_b128 v[230:233], v175 offset:36864
	ds_read_b128 v[234:237], v175 offset:37888
	ds_read_b128 v[238:241], v175 offset:38912
	ds_read_b128 v[242:245], v175 offset:39936
	global_load_lds_dwordx4 v[248:249], off
	v_lshl_add_u64 v[248:249], s[62:63], 0, v[132:133]
	s_mov_b32 m0, s47
	s_nop 0
	global_load_lds_dwordx4 v[248:249], off
	s_waitcnt vmcnt(8)
	s_waitcnt lgkmcnt(0)
	s_barrier
	s_setprio 1
	v_mfma_f32_16x16x32_bf16 v[124:127], v[178:181], v[210:213], v[124:127]
	v_mfma_f32_16x16x32_bf16 v[120:123], v[186:189], v[210:213], v[120:123]
	v_mfma_f32_16x16x32_bf16 v[116:119], v[178:181], v[222:225], v[116:119]
	v_mfma_f32_16x16x32_bf16 v[108:111], v[186:189], v[222:225], v[108:111]
	v_mfma_f32_16x16x32_bf16 v[100:103], v[178:181], v[230:233], v[100:103]
	v_mfma_f32_16x16x32_bf16 v[92:95], v[186:189], v[230:233], v[92:95]
	v_mfma_f32_16x16x32_bf16 v[84:87], v[178:181], v[238:241], v[84:87]
	v_mfma_f32_16x16x32_bf16 v[76:79], v[186:189], v[238:241], v[76:79]
	v_mfma_f32_16x16x32_bf16 v[124:127], v[182:185], v[218:221], v[124:127]
	v_mfma_f32_16x16x32_bf16 v[120:123], v[190:193], v[218:221], v[120:123]
	v_mfma_f32_16x16x32_bf16 v[116:119], v[182:185], v[226:229], v[116:119]
	v_mfma_f32_16x16x32_bf16 v[108:111], v[190:193], v[226:229], v[108:111]
	v_mfma_f32_16x16x32_bf16 v[100:103], v[182:185], v[234:237], v[100:103]
	v_mfma_f32_16x16x32_bf16 v[92:95], v[190:193], v[234:237], v[92:95]
	v_mfma_f32_16x16x32_bf16 v[84:87], v[182:185], v[242:245], v[84:87]
	v_mfma_f32_16x16x32_bf16 v[76:79], v[190:193], v[242:245], v[76:79]
	s_setprio 0
	s_setprio 1
	v_mfma_f32_16x16x32_bf16 v[112:115], v[194:197], v[210:213], v[112:115]
	v_mfma_f32_16x16x32_bf16 v[104:107], v[202:205], v[210:213], v[104:107]
	v_mfma_f32_16x16x32_bf16 v[96:99], v[194:197], v[222:225], v[96:99]
	v_mfma_f32_16x16x32_bf16 v[88:91], v[202:205], v[222:225], v[88:91]
	v_mfma_f32_16x16x32_bf16 v[80:83], v[194:197], v[230:233], v[80:83]
	v_mfma_f32_16x16x32_bf16 v[72:75], v[202:205], v[230:233], v[72:75]
	v_mfma_f32_16x16x32_bf16 v[68:71], v[194:197], v[238:241], v[68:71]
	v_mfma_f32_16x16x32_bf16 v[64:67], v[202:205], v[238:241], v[64:67]
	v_mfma_f32_16x16x32_bf16 v[112:115], v[198:201], v[218:221], v[112:115]
	v_mfma_f32_16x16x32_bf16 v[104:107], v[206:209], v[218:221], v[104:107]
	v_mfma_f32_16x16x32_bf16 v[96:99], v[198:201], v[226:229], v[96:99]
	v_mfma_f32_16x16x32_bf16 v[88:91], v[206:209], v[226:229], v[88:91]
	v_mfma_f32_16x16x32_bf16 v[80:83], v[198:201], v[234:237], v[80:83]
	v_mfma_f32_16x16x32_bf16 v[72:75], v[206:209], v[234:237], v[72:75]
	v_mfma_f32_16x16x32_bf16 v[68:71], v[198:201], v[242:245], v[68:71]
	v_mfma_f32_16x16x32_bf16 v[64:67], v[206:209], v[242:245], v[64:67]
	s_setprio 0
	s_barrier
	s_add_i32 s61, s61, s33
	v_lshl_add_u64 v[214:215], v[214:215], 0, s[20:21]
	s_mov_b32 m0, s61
	ds_read_b128 v[210:213], v175 offset:49152
	ds_read_b128 v[218:221], v175 offset:50176
	ds_read_b128 v[222:225], v175 offset:51200
	ds_read_b128 v[226:229], v175 offset:52224
	ds_read_b128 v[230:233], v175 offset:53248
	ds_read_b128 v[234:237], v175 offset:54272
	ds_read_b128 v[238:241], v175 offset:55296
	ds_read_b128 v[242:245], v175 offset:56320
	global_load_lds_dwordx4 v[214:215], off
	s_add_i32 m0, s61, 0x2000
	s_add_u32 s40, s40, 0x40080
	v_lshl_add_u64 v[214:215], v[246:247], 0, s[20:21]
	s_addc_u32 s41, s41, 0
	s_add_i32 s61, s64, s33
	global_load_lds_dwordx4 v[214:215], off
	v_lshl_add_u64 v[214:215], s[40:41], 0, v[130:131]
	s_mov_b32 m0, s61
	s_or_b32 s16, s16, 1
	global_load_lds_dwordx4 v[214:215], off
	v_lshl_add_u64 v[214:215], s[40:41], 0, v[134:135]
	s_add_i32 m0, s61, 0x2000
	s_lshl_b64 s[40:41], s[16:17], 7
	s_add_u32 s40, s43, s40
	s_addc_u32 s41, s42, s41
	global_load_lds_dwordx4 v[214:215], off
	v_lshl_add_u64 v[214:215], s[40:41], 0, v[128:129]
	s_mov_b32 m0, s49
	s_nop 0
	global_load_lds_dwordx4 v[214:215], off
	v_lshl_add_u64 v[214:215], s[40:41], 0, v[132:133]
	s_mov_b32 m0, s50
	s_nop 0
	global_load_lds_dwordx4 v[214:215], off
	s_waitcnt vmcnt(8)
	s_waitcnt lgkmcnt(0)
	s_barrier
	s_setprio 1
	v_mfma_f32_16x16x32_bf16 v[60:63], v[178:181], v[210:213], v[60:63]
	v_mfma_f32_16x16x32_bf16 v[56:59], v[186:189], v[210:213], v[56:59]
	v_mfma_f32_16x16x32_bf16 v[52:55], v[178:181], v[222:225], v[52:55]
	v_mfma_f32_16x16x32_bf16 v[44:47], v[186:189], v[222:225], v[44:47]
	v_mfma_f32_16x16x32_bf16 v[36:39], v[178:181], v[230:233], v[36:39]
	v_mfma_f32_16x16x32_bf16 v[28:31], v[186:189], v[230:233], v[28:31]
	v_mfma_f32_16x16x32_bf16 v[16:19], v[178:181], v[238:241], v[16:19]
	v_mfma_f32_16x16x32_bf16 v[8:11], v[186:189], v[238:241], v[8:11]
	v_mfma_f32_16x16x32_bf16 v[60:63], v[182:185], v[218:221], v[60:63]
	v_mfma_f32_16x16x32_bf16 v[56:59], v[190:193], v[218:221], v[56:59]
	v_mfma_f32_16x16x32_bf16 v[52:55], v[182:185], v[226:229], v[52:55]
	v_mfma_f32_16x16x32_bf16 v[44:47], v[190:193], v[226:229], v[44:47]
	v_mfma_f32_16x16x32_bf16 v[36:39], v[182:185], v[234:237], v[36:39]
	v_mfma_f32_16x16x32_bf16 v[28:31], v[190:193], v[234:237], v[28:31]
	v_mfma_f32_16x16x32_bf16 v[16:19], v[182:185], v[242:245], v[16:19]
	v_mfma_f32_16x16x32_bf16 v[8:11], v[190:193], v[242:245], v[8:11]
	s_setprio 0
	s_setprio 1
	v_mfma_f32_16x16x32_bf16 v[48:51], v[194:197], v[210:213], v[48:51]
	v_mfma_f32_16x16x32_bf16 v[40:43], v[202:205], v[210:213], v[40:43]
	v_mfma_f32_16x16x32_bf16 v[32:35], v[194:197], v[222:225], v[32:35]
	v_mfma_f32_16x16x32_bf16 v[24:27], v[202:205], v[222:225], v[24:27]
	v_mfma_f32_16x16x32_bf16 v[20:23], v[194:197], v[230:233], v[20:23]
	v_mfma_f32_16x16x32_bf16 v[12:15], v[202:205], v[230:233], v[12:15]
	v_mfma_f32_16x16x32_bf16 v[4:7], v[194:197], v[238:241], v[4:7]
	v_mfma_f32_16x16x32_bf16 v[0:3], v[202:205], v[238:241], v[0:3]
	v_mfma_f32_16x16x32_bf16 v[48:51], v[198:201], v[218:221], v[48:51]
	v_mfma_f32_16x16x32_bf16 v[40:43], v[206:209], v[218:221], v[40:43]
	v_mfma_f32_16x16x32_bf16 v[32:35], v[198:201], v[226:229], v[32:35]
	v_mfma_f32_16x16x32_bf16 v[24:27], v[206:209], v[226:229], v[24:27]
	v_mfma_f32_16x16x32_bf16 v[20:23], v[198:201], v[234:237], v[20:23]
	v_mfma_f32_16x16x32_bf16 v[12:15], v[206:209], v[234:237], v[12:15]
	v_mfma_f32_16x16x32_bf16 v[4:7], v[198:201], v[242:245], v[4:7]
	v_mfma_f32_16x16x32_bf16 v[0:3], v[206:209], v[242:245], v[0:3]
	s_setprio 0
	s_barrier
	s_add_u32 s38, s38, 0x100
	s_addc_u32 s39, s39, 0
	s_cmp_gt_u32 s59, 13
	s_mov_b32 s59, s60
	s_cbranch_scc0 .LBB0_599
	s_and_b64 vcc, exec, s[22:23]
	s_cbranch_vccz .LBB0_602
	s_barrier

.LBB0_678:
	ds_read_b128 v[144:147], v193
	ds_read_b128 v[148:151], v193 offset:1024
	ds_read_b128 v[152:155], v193 offset:2048
	ds_read_b128 v[156:159], v193 offset:3072
	ds_read_b128 v[160:163], v194
	ds_read_b128 v[164:167], v194 offset:1024
	ds_read_b128 v[168:171], v194 offset:2048
	ds_read_b128 v[172:175], v194 offset:3072
	s_cmp_eq_u32 s22, 0x7e04000
	s_cselect_b64 s[24:25], -1, 0
	s_and_b64 s[24:25], s[24:25], exec
	s_cselect_b32 s25, s9, s43
	s_cselect_b32 s24, s11, s42
	s_add_i32 s45, s44, 2
	s_cmp_eq_u32 s22, 0x7e04000
	s_cselect_b64 s[26:27], -1, 0
	s_and_b64 s[46:47], s[26:27], exec
	s_cselect_b32 s6, 0, s45
	s_and_b64 s[26:27], s[26:27], s[4:5]
	s_and_b64 s[26:27], s[26:27], exec
	s_cselect_b32 s26, s15, s21
	s_cselect_b32 s27, s14, s20
	v_lshl_add_u64 v[188:189], v[140:141], 0, s[22:23]
	s_add_i32 m0, s19, 0xc000
	ds_read_b128 v[176:179], v195
	ds_read_b128 v[180:183], v195 offset:1024
	ds_read_b128 v[184:187], v195 offset:2048
	ds_read_b128 v[196:199], v195 offset:3072
	ds_read_b128 v[200:203], v195 offset:4096
	ds_read_b128 v[204:207], v195 offset:5120
	ds_read_b128 v[208:211], v195 offset:6144
	ds_read_b128 v[212:215], v195 offset:7168
	global_load_lds_dwordx4 v[188:189], off
	v_lshl_add_u64 v[188:189], v[142:143], 0, s[22:23]
	s_add_i32 m0, s19, 0xe000
	s_nop 0
	global_load_lds_dwordx4 v[188:189], off
	s_waitcnt vmcnt(8)
	s_waitcnt lgkmcnt(0)
	s_barrier
	s_setprio 1
	v_mfma_f32_16x16x32_bf16 v[124:127], v[144:147], v[176:179], v[124:127]
	v_mfma_f32_16x16x32_bf16 v[120:123], v[152:155], v[176:179], v[120:123]
	v_mfma_f32_16x16x32_bf16 v[112:115], v[144:147], v[184:187], v[112:115]
	v_mfma_f32_16x16x32_bf16 v[104:107], v[152:155], v[184:187], v[104:107]
	v_mfma_f32_16x16x32_bf16 v[96:99], v[144:147], v[200:203], v[96:99]
	v_mfma_f32_16x16x32_bf16 v[88:91], v[152:155], v[200:203], v[88:91]
	v_mfma_f32_16x16x32_bf16 v[80:83], v[144:147], v[208:211], v[80:83]
	v_mfma_f32_16x16x32_bf16 v[72:75], v[152:155], v[208:211], v[72:75]
	v_mfma_f32_16x16x32_bf16 v[124:127], v[148:151], v[180:183], v[124:127]
	v_mfma_f32_16x16x32_bf16 v[120:123], v[156:159], v[180:183], v[120:123]
	v_mfma_f32_16x16x32_bf16 v[112:115], v[148:151], v[196:199], v[112:115]
	v_mfma_f32_16x16x32_bf16 v[104:107], v[156:159], v[196:199], v[104:107]
	v_mfma_f32_16x16x32_bf16 v[96:99], v[148:151], v[204:207], v[96:99]
	v_mfma_f32_16x16x32_bf16 v[88:91], v[156:159], v[204:207], v[88:91]
	v_mfma_f32_16x16x32_bf16 v[80:83], v[148:151], v[212:215], v[80:83]
	v_mfma_f32_16x16x32_bf16 v[72:75], v[156:159], v[212:215], v[72:75]
	s_setprio 0
	s_setprio 1
	v_mfma_f32_16x16x32_bf16 v[116:119], v[160:163], v[176:179], v[116:119]
	v_mfma_f32_16x16x32_bf16 v[108:111], v[168:171], v[176:179], v[108:111]
	v_mfma_f32_16x16x32_bf16 v[100:103], v[160:163], v[184:187], v[100:103]
	v_mfma_f32_16x16x32_bf16 v[92:95], v[168:171], v[184:187], v[92:95]
	v_mfma_f32_16x16x32_bf16 v[84:87], v[160:163], v[200:203], v[84:87]
	v_mfma_f32_16x16x32_bf16 v[76:79], v[168:171], v[200:203], v[76:79]
	v_mfma_f32_16x16x32_bf16 v[68:71], v[160:163], v[208:211], v[68:71]
	v_mfma_f32_16x16x32_bf16 v[64:67], v[168:171], v[208:211], v[64:67]
	v_mfma_f32_16x16x32_bf16 v[116:119], v[164:167], v[180:183], v[116:119]
	v_mfma_f32_16x16x32_bf16 v[108:111], v[172:175], v[180:183], v[108:111]
	v_mfma_f32_16x16x32_bf16 v[100:103], v[164:167], v[196:199], v[100:103]
	v_mfma_f32_16x16x32_bf16 v[92:95], v[172:175], v[196:199], v[92:95]
	v_mfma_f32_16x16x32_bf16 v[84:87], v[164:167], v[204:207], v[84:87]
	v_mfma_f32_16x16x32_bf16 v[76:79], v[172:175], v[204:207], v[76:79]
	v_mfma_f32_16x16x32_bf16 v[68:71], v[164:167], v[212:215], v[68:71]
	v_mfma_f32_16x16x32_bf16 v[64:67], v[172:175], v[212:215], v[64:67]
	s_setprio 0
	s_barrier
	s_add_i32 s46, s38, s29
	v_lshl_add_u64 v[188:189], s[24:25], 0, v[128:129]
	s_mov_b32 m0, s46
	ds_read_b128 v[176:179], v195 offset:16384
	ds_read_b128 v[180:183], v195 offset:17408
	ds_read_b128 v[184:187], v195 offset:18432
	ds_read_b128 v[196:199], v195 offset:19456
	ds_read_b128 v[200:203], v195 offset:20480
	ds_read_b128 v[204:207], v195 offset:21504
	ds_read_b128 v[208:211], v195 offset:22528
	ds_read_b128 v[212:215], v195 offset:23552
	global_load_lds_dwordx4 v[188:189], off
	s_add_i32 m0, s46, 0x2000
	s_add_u32 s46, s24, 0x4000
	v_lshl_add_u64 v[188:189], s[24:25], 0, v[130:131]
	s_addc_u32 s47, s25, 0
	s_add_i32 s48, s39, s29
	global_load_lds_dwordx4 v[188:189], off
	v_lshl_add_u64 v[188:189], s[46:47], 0, v[128:129]
	s_mov_b32 m0, s48
	s_nop 0
	global_load_lds_dwordx4 v[188:189], off
	v_lshl_add_u64 v[188:189], s[46:47], 0, v[130:131]
	s_add_i32 m0, s48, 0x2000
	s_lshl_b64 s[46:47], s[6:7], 21
	s_add_u32 s46, s27, s46
	s_addc_u32 s47, s26, s47
	global_load_lds_dwordx4 v[188:189], off
	v_lshl_add_u64 v[188:189], s[46:47], 0, v[128:129]
	s_mov_b32 m0, s19
	s_nop 0
	global_load_lds_dwordx4 v[188:189], off
	v_lshl_add_u64 v[188:189], s[46:47], 0, v[130:131]
	s_mov_b32 m0, s31
	s_nop 0
	global_load_lds_dwordx4 v[188:189], off
	s_waitcnt vmcnt(8)
	s_waitcnt lgkmcnt(0)
	s_barrier
	s_setprio 1
	v_mfma_f32_16x16x32_bf16 v[60:63], v[144:147], v[176:179], v[60:63]
	v_mfma_f32_16x16x32_bf16 v[56:59], v[152:155], v[176:179], v[56:59]
	v_mfma_f32_16x16x32_bf16 v[48:51], v[144:147], v[184:187], v[48:51]
	v_mfma_f32_16x16x32_bf16 v[40:43], v[152:155], v[184:187], v[40:43]
	v_mfma_f32_16x16x32_bf16 v[32:35], v[144:147], v[200:203], v[32:35]
	v_mfma_f32_16x16x32_bf16 v[24:27], v[152:155], v[200:203], v[24:27]
	v_mfma_f32_16x16x32_bf16 v[16:19], v[144:147], v[208:211], v[16:19]
	v_mfma_f32_16x16x32_bf16 v[8:11], v[152:155], v[208:211], v[8:11]
	v_mfma_f32_16x16x32_bf16 v[60:63], v[148:151], v[180:183], v[60:63]
	v_mfma_f32_16x16x32_bf16 v[56:59], v[156:159], v[180:183], v[56:59]
	v_mfma_f32_16x16x32_bf16 v[48:51], v[148:151], v[196:199], v[48:51]
	v_mfma_f32_16x16x32_bf16 v[40:43], v[156:159], v[196:199], v[40:43]
	v_mfma_f32_16x16x32_bf16 v[32:35], v[148:151], v[204:207], v[32:35]
	v_mfma_f32_16x16x32_bf16 v[24:27], v[156:159], v[204:207], v[24:27]
	v_mfma_f32_16x16x32_bf16 v[16:19], v[148:151], v[212:215], v[16:19]
	v_mfma_f32_16x16x32_bf16 v[8:11], v[156:159], v[212:215], v[8:11]
	s_setprio 0
	s_setprio 1
	v_mfma_f32_16x16x32_bf16 v[52:55], v[160:163], v[176:179], v[52:55]
	v_mfma_f32_16x16x32_bf16 v[44:47], v[168:171], v[176:179], v[44:47]
	v_mfma_f32_16x16x32_bf16 v[36:39], v[160:163], v[184:187], v[36:39]
	v_mfma_f32_16x16x32_bf16 v[28:31], v[168:171], v[184:187], v[28:31]
	v_mfma_f32_16x16x32_bf16 v[20:23], v[160:163], v[200:203], v[20:23]
	v_mfma_f32_16x16x32_bf16 v[12:15], v[168:171], v[200:203], v[12:15]
	v_mfma_f32_16x16x32_bf16 v[4:7], v[160:163], v[208:211], v[4:7]
	v_mfma_f32_16x16x32_bf16 v[0:3], v[168:171], v[208:211], v[0:3]
	v_mfma_f32_16x16x32_bf16 v[52:55], v[164:167], v[180:183], v[52:55]
	v_mfma_f32_16x16x32_bf16 v[44:47], v[172:175], v[180:183], v[44:47]
	v_mfma_f32_16x16x32_bf16 v[36:39], v[164:167], v[196:199], v[36:39]
	v_mfma_f32_16x16x32_bf16 v[28:31], v[172:175], v[196:199], v[28:31]
	v_mfma_f32_16x16x32_bf16 v[20:23], v[164:167], v[204:207], v[20:23]
	v_mfma_f32_16x16x32_bf16 v[12:15], v[172:175], v[204:207], v[12:15]
	v_mfma_f32_16x16x32_bf16 v[4:7], v[164:167], v[212:215], v[4:7]
	v_mfma_f32_16x16x32_bf16 v[0:3], v[172:175], v[212:215], v[0:3]
	s_setprio 0
	s_barrier
	s_add_i32 s48, 0, 0x18000
	s_add_i32 s49, 0, 0x1c000
	v_add_u32_e32 v156, s48, v191
	v_add_u32_e32 v172, s49, v191
	ds_read_b128 v[144:147], v156
	ds_read_b128 v[148:151], v156 offset:1024
	ds_read_b128 v[152:155], v156 offset:2048
	ds_read_b128 v[156:159], v156 offset:3072
	ds_read_b128 v[160:163], v172
	ds_read_b128 v[164:167], v172 offset:1024
	ds_read_b128 v[168:171], v172 offset:2048
	ds_read_b128 v[172:175], v172 offset:3072
	s_add_u32 s46, s46, 0x4000
	s_addc_u32 s47, s47, 0
	s_mov_b32 m0, s33
	v_lshl_add_u64 v[188:189], s[46:47], 0, v[128:129]
	ds_read_b128 v[176:179], v195 offset:32768
	ds_read_b128 v[180:183], v195 offset:33792
	ds_read_b128 v[184:187], v195 offset:34816
	ds_read_b128 v[196:199], v195 offset:35840
	ds_read_b128 v[200:203], v195 offset:36864
	ds_read_b128 v[204:207], v195 offset:37888
	ds_read_b128 v[208:211], v195 offset:38912
	ds_read_b128 v[212:215], v195 offset:39936
	global_load_lds_dwordx4 v[188:189], off
	v_lshl_add_u64 v[188:189], s[46:47], 0, v[130:131]
	s_mov_b32 m0, s34
	s_nop 0
	global_load_lds_dwordx4 v[188:189], off
	s_waitcnt vmcnt(8)
	s_waitcnt lgkmcnt(0)
	s_barrier
	s_setprio 1
	v_mfma_f32_16x16x32_bf16 v[124:127], v[144:147], v[176:179], v[124:127]
	v_mfma_f32_16x16x32_bf16 v[120:123], v[152:155], v[176:179], v[120:123]
	v_mfma_f32_16x16x32_bf16 v[112:115], v[144:147], v[184:187], v[112:115]
	v_mfma_f32_16x16x32_bf16 v[104:107], v[152:155], v[184:187], v[104:107]
	v_mfma_f32_16x16x32_bf16 v[96:99], v[144:147], v[200:203], v[96:99]
	v_mfma_f32_16x16x32_bf16 v[88:91], v[152:155], v[200:203], v[88:91]
	v_mfma_f32_16x16x32_bf16 v[80:83], v[144:147], v[208:211], v[80:83]
	v_mfma_f32_16x16x32_bf16 v[72:75], v[152:155], v[208:211], v[72:75]
	v_mfma_f32_16x16x32_bf16 v[124:127], v[148:151], v[180:183], v[124:127]
	v_mfma_f32_16x16x32_bf16 v[120:123], v[156:159], v[180:183], v[120:123]
	v_mfma_f32_16x16x32_bf16 v[112:115], v[148:151], v[196:199], v[112:115]
	v_mfma_f32_16x16x32_bf16 v[104:107], v[156:159], v[196:199], v[104:107]
	v_mfma_f32_16x16x32_bf16 v[96:99], v[148:151], v[204:207], v[96:99]
	v_mfma_f32_16x16x32_bf16 v[88:91], v[156:159], v[204:207], v[88:91]
	v_mfma_f32_16x16x32_bf16 v[80:83], v[148:151], v[212:215], v[80:83]
	v_mfma_f32_16x16x32_bf16 v[72:75], v[156:159], v[212:215], v[72:75]
	s_setprio 0
	s_setprio 1
	v_mfma_f32_16x16x32_bf16 v[116:119], v[160:163], v[176:179], v[116:119]
	v_mfma_f32_16x16x32_bf16 v[108:111], v[168:171], v[176:179], v[108:111]
	v_mfma_f32_16x16x32_bf16 v[100:103], v[160:163], v[184:187], v[100:103]
	v_mfma_f32_16x16x32_bf16 v[92:95], v[168:171], v[184:187], v[92:95]
	v_mfma_f32_16x16x32_bf16 v[84:87], v[160:163], v[200:203], v[84:87]
	v_mfma_f32_16x16x32_bf16 v[76:79], v[168:171], v[200:203], v[76:79]
	v_mfma_f32_16x16x32_bf16 v[68:71], v[160:163], v[208:211], v[68:71]
	v_mfma_f32_16x16x32_bf16 v[64:67], v[168:171], v[208:211], v[64:67]
	v_mfma_f32_16x16x32_bf16 v[116:119], v[164:167], v[180:183], v[116:119]
	v_mfma_f32_16x16x32_bf16 v[108:111], v[172:175], v[180:183], v[108:111]
	v_mfma_f32_16x16x32_bf16 v[100:103], v[164:167], v[196:199], v[100:103]
	v_mfma_f32_16x16x32_bf16 v[92:95], v[172:175], v[196:199], v[92:95]
	v_mfma_f32_16x16x32_bf16 v[84:87], v[164:167], v[204:207], v[84:87]
	v_mfma_f32_16x16x32_bf16 v[76:79], v[172:175], v[204:207], v[76:79]
	v_mfma_f32_16x16x32_bf16 v[68:71], v[164:167], v[212:215], v[68:71]
	v_mfma_f32_16x16x32_bf16 v[64:67], v[172:175], v[212:215], v[64:67]
	s_setprio 0
	s_barrier
	s_add_u32 s46, s24, 0x20000
	s_addc_u32 s47, s25, 0
	s_add_i32 s48, s48, s29
	v_lshl_add_u64 v[188:189], s[46:47], 0, v[128:129]
	s_mov_b32 m0, s48
	ds_read_b128 v[176:179], v195 offset:49152
	ds_read_b128 v[180:183], v195 offset:50176
	ds_read_b128 v[184:187], v195 offset:51200
	ds_read_b128 v[196:199], v195 offset:52224
	ds_read_b128 v[200:203], v195 offset:53248
	ds_read_b128 v[204:207], v195 offset:54272
	ds_read_b128 v[208:211], v195 offset:55296
	ds_read_b128 v[212:215], v195 offset:56320
	global_load_lds_dwordx4 v[188:189], off
	s_add_i32 m0, s48, 0x2000
	s_add_u32 s24, s24, 0x24000
	v_lshl_add_u64 v[188:189], s[46:47], 0, v[130:131]
	s_addc_u32 s25, s25, 0
	s_add_i32 s46, s49, s29
	global_load_lds_dwordx4 v[188:189], off
	v_lshl_add_u64 v[188:189], s[24:25], 0, v[128:129]
	s_mov_b32 m0, s46
	s_or_b32 s6, s6, 1
	global_load_lds_dwordx4 v[188:189], off
	v_lshl_add_u64 v[188:189], s[24:25], 0, v[130:131]
	s_add_i32 m0, s46, 0x2000
	s_lshl_b64 s[24:25], s[6:7], 21
	s_add_u32 s24, s27, s24
	s_addc_u32 s25, s26, s25
	global_load_lds_dwordx4 v[188:189], off
	v_lshl_add_u64 v[188:189], s[24:25], 0, v[128:129]
	s_mov_b32 m0, s36
	s_nop 0
	global_load_lds_dwordx4 v[188:189], off
	v_lshl_add_u64 v[188:189], s[24:25], 0, v[130:131]
	s_mov_b32 m0, s37
	s_nop 0
	global_load_lds_dwordx4 v[188:189], off
	s_waitcnt vmcnt(8)
	s_waitcnt lgkmcnt(0)
	s_barrier
	s_setprio 1
	v_mfma_f32_16x16x32_bf16 v[60:63], v[144:147], v[176:179], v[60:63]
	v_mfma_f32_16x16x32_bf16 v[56:59], v[152:155], v[176:179], v[56:59]
	v_mfma_f32_16x16x32_bf16 v[48:51], v[144:147], v[184:187], v[48:51]
	v_mfma_f32_16x16x32_bf16 v[40:43], v[152:155], v[184:187], v[40:43]
	v_mfma_f32_16x16x32_bf16 v[32:35], v[144:147], v[200:203], v[32:35]
	v_mfma_f32_16x16x32_bf16 v[24:27], v[152:155], v[200:203], v[24:27]
	v_mfma_f32_16x16x32_bf16 v[16:19], v[144:147], v[208:211], v[16:19]
	v_mfma_f32_16x16x32_bf16 v[8:11], v[152:155], v[208:211], v[8:11]
	v_mfma_f32_16x16x32_bf16 v[60:63], v[148:151], v[180:183], v[60:63]
	v_mfma_f32_16x16x32_bf16 v[56:59], v[156:159], v[180:183], v[56:59]
	v_mfma_f32_16x16x32_bf16 v[48:51], v[148:151], v[196:199], v[48:51]
	v_mfma_f32_16x16x32_bf16 v[40:43], v[156:159], v[196:199], v[40:43]
	v_mfma_f32_16x16x32_bf16 v[32:35], v[148:151], v[204:207], v[32:35]
	v_mfma_f32_16x16x32_bf16 v[24:27], v[156:159], v[204:207], v[24:27]
	v_mfma_f32_16x16x32_bf16 v[16:19], v[148:151], v[212:215], v[16:19]
	v_mfma_f32_16x16x32_bf16 v[8:11], v[156:159], v[212:215], v[8:11]
	s_setprio 0
	s_setprio 1
	v_mfma_f32_16x16x32_bf16 v[52:55], v[160:163], v[176:179], v[52:55]
	v_mfma_f32_16x16x32_bf16 v[44:47], v[168:171], v[176:179], v[44:47]
	v_mfma_f32_16x16x32_bf16 v[36:39], v[160:163], v[184:187], v[36:39]
	v_mfma_f32_16x16x32_bf16 v[28:31], v[168:171], v[184:187], v[28:31]
	v_mfma_f32_16x16x32_bf16 v[20:23], v[160:163], v[200:203], v[20:23]
	v_mfma_f32_16x16x32_bf16 v[12:15], v[168:171], v[200:203], v[12:15]
	v_mfma_f32_16x16x32_bf16 v[4:7], v[160:163], v[208:211], v[4:7]
	v_mfma_f32_16x16x32_bf16 v[0:3], v[168:171], v[208:211], v[0:3]
	v_mfma_f32_16x16x32_bf16 v[52:55], v[164:167], v[180:183], v[52:55]
	v_mfma_f32_16x16x32_bf16 v[44:47], v[172:175], v[180:183], v[44:47]
	v_mfma_f32_16x16x32_bf16 v[36:39], v[164:167], v[196:199], v[36:39]
	v_mfma_f32_16x16x32_bf16 v[28:31], v[172:175], v[196:199], v[28:31]
	v_mfma_f32_16x16x32_bf16 v[20:23], v[164:167], v[204:207], v[20:23]
	v_mfma_f32_16x16x32_bf16 v[12:15], v[172:175], v[204:207], v[12:15]
	v_mfma_f32_16x16x32_bf16 v[4:7], v[164:167], v[212:215], v[4:7]
	v_mfma_f32_16x16x32_bf16 v[0:3], v[172:175], v[212:215], v[0:3]
	s_setprio 0
	s_barrier
	s_add_u32 s22, s22, 0x400000
	s_addc_u32 s23, s23, 0
	s_add_u32 s42, s42, 0x40000
	s_addc_u32 s43, s43, 0
	s_cmp_gt_u32 s44, 61
	s_mov_b32 s44, s45
	s_cbranch_scc0 .LBB0_678
	v_lshl_or_b32 v142, s41, 8, v192
	v_lshl_add_u32 v144, s18, 8, v190
	v_ashrrev_i32_e32 v143, 31, v142
	v_ashrrev_i32_e32 v145, 31, v144
	v_lshl_add_u64 v[146:147], v[142:143], 1, s[12:13]
	v_lshlrev_b64 v[140:141], 11, v[144:145]
	v_lshl_add_u64 v[140:141], v[146:147], 0, v[140:141]
	global_load_dwordx2 v[196:197], v[140:141], off
	global_load_dwordx2 v[198:199], v[140:141], off offset:32
	global_load_dwordx2 v[200:201], v[140:141], off offset:256
	v_or_b32_e32 v202, 16, v144
	v_ashrrev_i32_e32 v203, 31, v202
	global_load_dwordx2 v[204:205], v[140:141], off offset:288
	v_lshlrev_b64 v[140:141], 11, v[202:203]
	v_lshl_add_u64 v[148:149], v[146:147], 0, v[140:141]
	global_load_dwordx2 v[206:207], v[148:149], off
	global_load_dwordx2 v[208:209], v[148:149], off offset:32
	global_load_dwordx2 v[210:211], v[148:149], off offset:256
	global_load_dwordx2 v[212:213], v[148:149], off offset:288
	v_or_b32_e32 v188, 32, v144
	v_or_b32_e32 v178, 48, v144
	v_add_u32_e32 v168, 0x80, v144
	v_add_u32_e32 v160, 0x90, v144
	v_add_u32_e32 v150, 0xa0, v144
	v_add_u32_e32 v140, 0xb0, v144
	v_ashrrev_i32_e32 v189, 31, v188
	v_ashrrev_i32_e32 v179, 31, v178
	v_ashrrev_i32_e32 v169, 31, v168
	v_ashrrev_i32_e32 v161, 31, v160
	v_ashrrev_i32_e32 v151, 31, v150
	v_ashrrev_i32_e32 v141, 31, v140
	v_lshlrev_b64 v[152:153], 12, v[144:145]
	v_lshlrev_b64 v[144:145], 2, v[142:143]
	v_lshlrev_b64 v[142:143], 11, v[188:189]
	v_lshlrev_b64 v[154:155], 11, v[178:179]
	v_lshlrev_b64 v[156:157], 11, v[168:169]
	v_lshlrev_b64 v[158:159], 11, v[160:161]
	v_lshlrev_b64 v[162:163], 11, v[150:151]
	v_lshlrev_b64 v[164:165], 11, v[140:141]
	v_lshl_add_u64 v[152:153], s[78:79], 0, v[152:153]
	v_lshl_add_u64 v[142:143], v[146:147], 0, v[142:143]
	v_lshl_add_u64 v[154:155], v[146:147], 0, v[154:155]
	v_lshl_add_u64 v[156:157], v[146:147], 0, v[156:157]
	v_lshl_add_u64 v[158:159], v[146:147], 0, v[158:159]
	v_lshl_add_u64 v[148:149], v[146:147], 0, v[162:163]
	v_lshl_add_u64 v[214:215], v[146:147], 0, v[164:165]
	v_lshl_add_u64 v[216:217], v[152:153], 0, v[144:145]
	global_load_dwordx2 v[218:219], v[142:143], off
	global_load_dwordx2 v[220:221], v[142:143], off offset:32
	global_load_dwordx2 v[222:223], v[142:143], off offset:256
	global_load_dwordx2 v[224:225], v[142:143], off offset:288
	global_load_dwordx2 v[226:227], v[154:155], off
	global_load_dwordx2 v[228:229], v[154:155], off offset:32
	global_load_dwordx2 v[186:187], v[154:155], off offset:256
	global_load_dwordx2 v[184:185], v[154:155], off offset:288
	global_load_dwordx2 v[182:183], v[156:157], off
	global_load_dwordx2 v[180:181], v[156:157], off offset:32
	global_load_dwordx2 v[176:177], v[156:157], off offset:256
	global_load_dwordx2 v[174:175], v[156:157], off offset:288
	global_load_dwordx2 v[172:173], v[158:159], off
	global_load_dwordx2 v[170:171], v[158:159], off offset:32
	global_load_dwordx2 v[166:167], v[158:159], off offset:256
	global_load_dwordx2 v[164:165], v[158:159], off offset:288
	global_load_dwordx2 v[162:163], v[148:149], off
	s_nop 0
	global_load_dwordx2 v[158:159], v[148:149], off offset:32
	global_load_dwordx2 v[156:157], v[148:149], off offset:256
	global_load_dwordx2 v[154:155], v[148:149], off offset:288
	global_load_dwordx2 v[152:153], v[214:215], off
	s_nop 0
	global_load_dwordx2 v[148:149], v[214:215], off offset:32
	global_load_dwordx2 v[146:147], v[214:215], off offset:256
	global_load_dwordx2 v[142:143], v[214:215], off offset:288
	s_and_b64 vcc, exec, s[0:1]
	s_mov_b32 s41, s8
	s_mov_b32 s18, s10
	s_mov_b64 s[22:23], s[16:17]
	s_mov_b64 s[20:21], s[14:15]
	s_waitcnt vmcnt(0)
	v_lshlrev_b32_e32 v214, 16, v196
	v_and_b32_e32 v215, 0xffff0000, v196
	v_lshlrev_b32_e32 v196, 16, v197
	v_and_b32_e32 v197, 0xffff0000, v197
	v_lshlrev_b32_e32 v230, 16, v198
	v_and_b32_e32 v231, 0xffff0000, v198
	v_lshlrev_b32_e32 v198, 16, v199
	v_and_b32_e32 v199, 0xffff0000, v199
	v_pk_add_f32 v[126:127], v[126:127], v[196:197]
	v_pk_add_f32 v[124:125], v[124:125], v[214:215]
	v_pk_add_f32 v[120:121], v[120:121], v[230:231]
	v_lshlrev_b32_e32 v232, 16, v200
	v_and_b32_e32 v233, 0xffff0000, v200
	v_pk_add_f32 v[122:123], v[122:123], v[198:199]
	global_store_dwordx4 v[216:217], v[124:127], off
	global_store_dwordx4 v[216:217], v[120:123], off offset:64
	v_pk_add_f32 v[116:117], v[116:117], v[232:233]
	s_nop 0
	v_lshlrev_b32_e32 v120, 16, v201
	v_and_b32_e32 v121, 0xffff0000, v201
	v_pk_add_f32 v[118:119], v[118:119], v[120:121]
	global_store_dwordx4 v[216:217], v[116:119], off offset:512
	s_nop 1
	v_lshlrev_b32_e32 v116, 16, v204
	v_and_b32_e32 v117, 0xffff0000, v204
	v_lshlrev_b32_e32 v118, 16, v205
	v_and_b32_e32 v119, 0xffff0000, v205
	v_pk_add_f32 v[110:111], v[110:111], v[118:119]
	v_pk_add_f32 v[108:109], v[108:109], v[116:117]
	global_store_dwordx4 v[216:217], v[108:111], off offset:576
	v_lshlrev_b64 v[116:117], 12, v[202:203]
	s_nop 0
	v_lshlrev_b32_e32 v108, 16, v206
	v_and_b32_e32 v109, 0xffff0000, v206
	v_lshlrev_b32_e32 v110, 16, v207
	v_and_b32_e32 v111, 0xffff0000, v207
	v_pk_add_f32 v[108:109], v[112:113], v[108:109]
	v_lshl_add_u64 v[112:113], s[78:79], 0, v[116:117]
	v_pk_add_f32 v[110:111], v[114:115], v[110:111]
	v_lshl_add_u64 v[112:113], v[112:113], 0, v[144:145]
	global_store_dwordx4 v[112:113], v[108:111], off
	s_nop 1
	v_lshlrev_b32_e32 v108, 16, v208
	v_and_b32_e32 v109, 0xffff0000, v208
	v_lshlrev_b32_e32 v110, 16, v209
	v_and_b32_e32 v111, 0xffff0000, v209
	v_pk_add_f32 v[106:107], v[106:107], v[110:111]
	v_pk_add_f32 v[104:105], v[104:105], v[108:109]
	global_store_dwordx4 v[112:113], v[104:107], off offset:64
	s_nop 1
	v_lshlrev_b32_e32 v104, 16, v210
	v_and_b32_e32 v105, 0xffff0000, v210
	v_lshlrev_b32_e32 v106, 16, v211
	v_and_b32_e32 v107, 0xffff0000, v211
	v_pk_add_f32 v[102:103], v[102:103], v[106:107]
	v_pk_add_f32 v[100:101], v[100:101], v[104:105]
	global_store_dwordx4 v[112:113], v[100:103], off offset:512
	s_nop 1
	v_lshlrev_b32_e32 v100, 16, v212
	v_and_b32_e32 v101, 0xffff0000, v212
	v_lshlrev_b32_e32 v102, 16, v213
	v_and_b32_e32 v103, 0xffff0000, v213
	v_pk_add_f32 v[94:95], v[94:95], v[102:103]
	v_pk_add_f32 v[92:93], v[92:93], v[100:101]
	global_store_dwordx4 v[112:113], v[92:95], off offset:576
	v_lshlrev_b64 v[100:101], 12, v[188:189]
	s_nop 0
	v_lshlrev_b32_e32 v92, 16, v218
	v_and_b32_e32 v93, 0xffff0000, v218
	v_lshlrev_b32_e32 v94, 16, v219
	v_and_b32_e32 v95, 0xffff0000, v219
	v_pk_add_f32 v[92:93], v[96:97], v[92:93]
	v_lshl_add_u64 v[96:97], s[78:79], 0, v[100:101]
	v_pk_add_f32 v[94:95], v[98:99], v[94:95]
	v_lshl_add_u64 v[96:97], v[96:97], 0, v[144:145]
	global_store_dwordx4 v[96:97], v[92:95], off
	s_nop 1
	v_lshlrev_b32_e32 v92, 16, v220
	v_and_b32_e32 v93, 0xffff0000, v220
	v_lshlrev_b32_e32 v94, 16, v221
	v_and_b32_e32 v95, 0xffff0000, v221
	v_pk_add_f32 v[90:91], v[90:91], v[94:95]
	v_pk_add_f32 v[88:89], v[88:89], v[92:93]
	global_store_dwordx4 v[96:97], v[88:91], off offset:64
	s_nop 1
	v_lshlrev_b32_e32 v88, 16, v222
	v_and_b32_e32 v89, 0xffff0000, v222
	v_lshlrev_b32_e32 v90, 16, v223
	v_and_b32_e32 v91, 0xffff0000, v223
	v_pk_add_f32 v[86:87], v[86:87], v[90:91]
	v_pk_add_f32 v[84:85], v[84:85], v[88:89]
	global_store_dwordx4 v[96:97], v[84:87], off offset:512
	s_nop 1
	v_lshlrev_b32_e32 v84, 16, v224
	v_and_b32_e32 v85, 0xffff0000, v224
	v_lshlrev_b32_e32 v86, 16, v225
	v_and_b32_e32 v87, 0xffff0000, v225
	v_pk_add_f32 v[78:79], v[78:79], v[86:87]
	v_pk_add_f32 v[76:77], v[76:77], v[84:85]
	global_store_dwordx4 v[96:97], v[76:79], off offset:576
	v_lshlrev_b64 v[84:85], 12, v[178:179]
	s_nop 0
	v_lshlrev_b32_e32 v76, 16, v226
	v_and_b32_e32 v77, 0xffff0000, v226
	v_lshlrev_b32_e32 v78, 16, v227
	v_and_b32_e32 v79, 0xffff0000, v227
	v_pk_add_f32 v[76:77], v[80:81], v[76:77]
	v_lshl_add_u64 v[80:81], s[78:79], 0, v[84:85]
	v_pk_add_f32 v[78:79], v[82:83], v[78:79]
	v_lshl_add_u64 v[80:81], v[80:81], 0, v[144:145]
	global_store_dwordx4 v[80:81], v[76:79], off
	s_nop 1
	v_lshlrev_b32_e32 v76, 16, v228
	v_and_b32_e32 v77, 0xffff0000, v228
	v_lshlrev_b32_e32 v78, 16, v229
	v_and_b32_e32 v79, 0xffff0000, v229
	v_pk_add_f32 v[74:75], v[74:75], v[78:79]
	v_pk_add_f32 v[72:73], v[72:73], v[76:77]
	global_store_dwordx4 v[80:81], v[72:75], off offset:64
	s_nop 1
	v_lshlrev_b32_e32 v72, 16, v186
	v_and_b32_e32 v73, 0xffff0000, v186
	v_lshlrev_b32_e32 v74, 16, v187
	v_and_b32_e32 v75, 0xffff0000, v187
	v_pk_add_f32 v[70:71], v[70:71], v[74:75]
	v_pk_add_f32 v[68:69], v[68:69], v[72:73]
	global_store_dwordx4 v[80:81], v[68:71], off offset:512
	s_nop 1
	v_lshlrev_b32_e32 v68, 16, v184
	v_and_b32_e32 v69, 0xffff0000, v184
	v_lshlrev_b32_e32 v70, 16, v185
	v_and_b32_e32 v71, 0xffff0000, v185
	v_pk_add_f32 v[66:67], v[66:67], v[70:71]
	v_pk_add_f32 v[64:65], v[64:65], v[68:69]
	global_store_dwordx4 v[80:81], v[64:67], off offset:576
	v_lshlrev_b32_e32 v68, 16, v183
	v_and_b32_e32 v69, 0xffff0000, v183
	v_lshlrev_b64 v[64:65], 12, v[168:169]
	v_lshlrev_b32_e32 v66, 16, v182
	v_and_b32_e32 v67, 0xffff0000, v182
	v_lshl_add_u64 v[64:65], s[78:79], 0, v[64:65]
	v_pk_add_f32 v[62:63], v[62:63], v[68:69]
	v_pk_add_f32 v[60:61], v[60:61], v[66:67]
	v_lshl_add_u64 v[64:65], v[64:65], 0, v[144:145]
	global_store_dwordx4 v[64:65], v[60:63], off
	s_nop 1
	v_lshlrev_b32_e32 v60, 16, v180
	v_and_b32_e32 v61, 0xffff0000, v180
	v_lshlrev_b32_e32 v62, 16, v181
	v_and_b32_e32 v63, 0xffff0000, v181
	v_pk_add_f32 v[58:59], v[58:59], v[62:63]
	v_pk_add_f32 v[56:57], v[56:57], v[60:61]
	global_store_dwordx4 v[64:65], v[56:59], off offset:64
	s_nop 1
	v_lshlrev_b32_e32 v56, 16, v176
	v_and_b32_e32 v57, 0xffff0000, v176
	v_lshlrev_b32_e32 v58, 16, v177
	v_and_b32_e32 v59, 0xffff0000, v177
	v_pk_add_f32 v[54:55], v[54:55], v[58:59]
	v_pk_add_f32 v[52:53], v[52:53], v[56:57]
	global_store_dwordx4 v[64:65], v[52:55], off offset:512
	s_nop 1
	v_lshlrev_b32_e32 v52, 16, v174
	v_and_b32_e32 v53, 0xffff0000, v174
	v_lshlrev_b32_e32 v54, 16, v175
	v_and_b32_e32 v55, 0xffff0000, v175
	v_pk_add_f32 v[46:47], v[46:47], v[54:55]
	v_pk_add_f32 v[44:45], v[44:45], v[52:53]
	global_store_dwordx4 v[64:65], v[44:47], off offset:576
	v_lshlrev_b64 v[52:53], 12, v[160:161]
	s_nop 0
	v_lshlrev_b32_e32 v44, 16, v172
	v_and_b32_e32 v45, 0xffff0000, v172
	v_lshlrev_b32_e32 v46, 16, v173
	v_and_b32_e32 v47, 0xffff0000, v173
	v_pk_add_f32 v[44:45], v[48:49], v[44:45]
	v_lshl_add_u64 v[48:49], s[78:79], 0, v[52:53]
	v_pk_add_f32 v[46:47], v[50:51], v[46:47]
	v_lshl_add_u64 v[48:49], v[48:49], 0, v[144:145]
	global_store_dwordx4 v[48:49], v[44:47], off
	s_nop 1
	v_lshlrev_b32_e32 v44, 16, v170
	v_and_b32_e32 v45, 0xffff0000, v170
	v_lshlrev_b32_e32 v46, 16, v171
	v_and_b32_e32 v47, 0xffff0000, v171
	v_pk_add_f32 v[42:43], v[42:43], v[46:47]
	v_pk_add_f32 v[40:41], v[40:41], v[44:45]
	global_store_dwordx4 v[48:49], v[40:43], off offset:64
	s_nop 1
	v_lshlrev_b32_e32 v40, 16, v166
	v_and_b32_e32 v41, 0xffff0000, v166
	v_lshlrev_b32_e32 v42, 16, v167
	v_and_b32_e32 v43, 0xffff0000, v167
	v_pk_add_f32 v[38:39], v[38:39], v[42:43]
	v_pk_add_f32 v[36:37], v[36:37], v[40:41]
	global_store_dwordx4 v[48:49], v[36:39], off offset:512
	s_nop 1
	v_lshlrev_b32_e32 v36, 16, v164
	v_and_b32_e32 v37, 0xffff0000, v164
	v_lshlrev_b32_e32 v38, 16, v165
	v_and_b32_e32 v39, 0xffff0000, v165
	v_pk_add_f32 v[30:31], v[30:31], v[38:39]
	v_pk_add_f32 v[28:29], v[28:29], v[36:37]
	global_store_dwordx4 v[48:49], v[28:31], off offset:576
	v_lshlrev_b64 v[36:37], 12, v[150:151]
	s_nop 0
	v_lshlrev_b32_e32 v28, 16, v162
	v_and_b32_e32 v29, 0xffff0000, v162
	v_lshlrev_b32_e32 v30, 16, v163
	v_and_b32_e32 v31, 0xffff0000, v163
	v_pk_add_f32 v[28:29], v[32:33], v[28:29]
	v_lshl_add_u64 v[32:33], s[78:79], 0, v[36:37]
	v_pk_add_f32 v[30:31], v[34:35], v[30:31]
	v_lshl_add_u64 v[32:33], v[32:33], 0, v[144:145]
	global_store_dwordx4 v[32:33], v[28:31], off
	s_nop 1
	v_lshlrev_b32_e32 v28, 16, v158
	v_and_b32_e32 v29, 0xffff0000, v158
	v_lshlrev_b32_e32 v30, 16, v159
	v_and_b32_e32 v31, 0xffff0000, v159
	v_pk_add_f32 v[26:27], v[26:27], v[30:31]
	v_pk_add_f32 v[24:25], v[24:25], v[28:29]
	global_store_dwordx4 v[32:33], v[24:27], off offset:64
	s_nop 1
	v_lshlrev_b32_e32 v24, 16, v156
	v_and_b32_e32 v25, 0xffff0000, v156
	v_lshlrev_b32_e32 v26, 16, v157
	v_and_b32_e32 v27, 0xffff0000, v157
	v_pk_add_f32 v[22:23], v[22:23], v[26:27]
	v_pk_add_f32 v[20:21], v[20:21], v[24:25]
	global_store_dwordx4 v[32:33], v[20:23], off offset:512
	s_nop 1
	v_lshlrev_b32_e32 v20, 16, v154
	v_and_b32_e32 v21, 0xffff0000, v154
	v_lshlrev_b32_e32 v22, 16, v155
	v_and_b32_e32 v23, 0xffff0000, v155
	v_pk_add_f32 v[14:15], v[14:15], v[22:23]
	v_pk_add_f32 v[12:13], v[12:13], v[20:21]
	global_store_dwordx4 v[32:33], v[12:15], off offset:576
	v_lshlrev_b64 v[20:21], 12, v[140:141]
	s_nop 0
	v_lshlrev_b32_e32 v12, 16, v152
	v_and_b32_e32 v13, 0xffff0000, v152
	v_lshlrev_b32_e32 v14, 16, v153
	v_and_b32_e32 v15, 0xffff0000, v153
	v_pk_add_f32 v[12:13], v[16:17], v[12:13]
	v_lshl_add_u64 v[16:17], s[78:79], 0, v[20:21]
	v_pk_add_f32 v[14:15], v[18:19], v[14:15]
	v_lshl_add_u64 v[16:17], v[16:17], 0, v[144:145]
	global_store_dwordx4 v[16:17], v[12:15], off
	s_nop 1
	v_lshlrev_b32_e32 v12, 16, v148
	v_and_b32_e32 v13, 0xffff0000, v148
	v_lshlrev_b32_e32 v14, 16, v149
	v_and_b32_e32 v15, 0xffff0000, v149
	v_pk_add_f32 v[10:11], v[10:11], v[14:15]
	v_pk_add_f32 v[8:9], v[8:9], v[12:13]
	global_store_dwordx4 v[16:17], v[8:11], off offset:64
	s_nop 1
	v_lshlrev_b32_e32 v8, 16, v146
	v_and_b32_e32 v9, 0xffff0000, v146
	v_lshlrev_b32_e32 v10, 16, v147
	v_and_b32_e32 v11, 0xffff0000, v147
	v_pk_add_f32 v[6:7], v[6:7], v[10:11]
	v_pk_add_f32 v[4:5], v[4:5], v[8:9]
	global_store_dwordx4 v[16:17], v[4:7], off offset:512
	s_nop 1
	v_lshlrev_b32_e32 v4, 16, v142
	v_and_b32_e32 v5, 0xffff0000, v142
	v_lshlrev_b32_e32 v6, 16, v143
	v_and_b32_e32 v7, 0xffff0000, v143
	v_pk_add_f32 v[2:3], v[2:3], v[6:7]
	v_pk_add_f32 v[0:1], v[0:1], v[4:5]
	global_store_dwordx4 v[16:17], v[0:3], off offset:576
	s_cbranch_vccz .LBB0_671
	s_waitcnt vmcnt(0)
	s_cmpk_gt_u32 s28, 0xff
	s_cbranch_scc1 .LBB0_682
	s_barrier
